# EpiUp epilogue: 254 three-deep v_cndmask index chains replaced by one v_cndmask on the lane mask fr>=k, 247 zero-inits before full-row DPP movs removed, hazard distances re-padded; plus final_c8
# speedup vs baseline: 1.0093x; 1.0093x over previous
; __device__ __forceinline__ float siluf(float x) { return x * __builtin_amdgcn_rcpf(1.f + __expf(-x)); }
;     __device__ __forceinline__ void operator()(const f32x4 (&acc)[2][2][4][2], const pg8::Unit& u, int wr, int wc, int fr, int fq) const {
;     ...
;         for (int cp = 0; cp < 4; ++cp) {
;             const int chp = ch0 + 2 * cp;
;             const f32x2 wa0 = *(const f32x2*)(wconv + chp), wa1 = *(const f32x2*)(wconv + NUP + chp), wa2 = *(const f32x2*)(wconv + 2 * NUP + chp), ba = *(const f32x2*)(bconv + chp);
;             const f32x2 wb0 = *(const f32x2*)(wconv + DFF + chp), wb1 = *(const f32x2*)(wconv + NUP + DFF + chp), wb2 = *(const f32x2*)(wconv + 2 * NUP + DFF + chp), bb = *(const f32x2*)(bconv + DFF + chp);
; #pragma unroll
;             for (int ai = 0; ai < 2; ++ai) {
;                 float rr[4][2];
; #pragma unroll
;                 for (int ii = 0; ii < 2; ++ii) {
;                     const int c8 = 2 * cp + ii, n = c8 >> 2, i = c8 & 3;
;                     float ua[4], ub[4], r1a[4], r2a[4], r1b[4], r2b[4];
; #pragma unroll
;                     for (int m = 0; m < 4; ++m) { ua[m] = acc[ai][0][m][n][i]; ub[m] = acc[ai][1][m][n][i];
;                         r1a[m] = dpp_ror<0x121>(ua[m]); r2a[m] = dpp_ror<0x122>(ua[m]); r1b[m] = dpp_ror<0x121>(ub[m]); r2b[m] = dpp_ror<0x122>(ub[m]); }
; #pragma unroll
;                     for (int m = 0; m < 4; ++m) {
;                         const float p1a = fr >= 1 ? r1a[m] : r1a[(m + 3) & 3], p2a = fr >= 2 ? r2a[m] : r2a[(m + 3) & 3];
;                         const float p1b = fr >= 1 ? r1b[m] : r1b[(m + 3) & 3], p2b = fr >= 2 ? r2b[m] : r2b[(m + 3) & 3];
;                         const float ca = ba[ii] + wa2[ii] * ua[m] + wa1[ii] * p1a + wa0[ii] * p2a;
;                         const float cb = bb[ii] + wb2[ii] * ub[m] + wb1[ii] * p1b + wb0[ii] * p2b;
;                         rr[m][ii] = siluf(ca) * cb;
.LBB0_2211:
	v_cmp_ne_u32_e64 s[98:99], 0, v129
	v_cmp_lt_u32_e64 s[100:101], 1, v129
	v_lshl_or_b32 v162, s16, 7, v147
	v_ashrrev_i32_e32 v163, 31, v162
	v_lshlrev_b64 v[170:171], 2, v[162:163]
	v_readlane_b32 s12, v255, 17
	v_readlane_b32 s14, v255, 19
	v_readlane_b32 s15, v255, 20
	v_readlane_b32 s16, v255, 21
	v_readlane_b32 s17, v255, 22
	v_readlane_b32 s22, v255, 27
	v_readlane_b32 s23, v255, 28
	v_readlane_b32 s24, v255, 29
	v_readlane_b32 s25, v255, 30
	v_lshl_add_u64 v[166:167], s[80:81], 0, v[170:171]
	s_mov_b64 s[14:15], s[22:23]
	s_mov_b64 s[16:17], s[24:25]
	global_load_dwordx2 v[174:175], v[166:167], off
	v_lshl_add_u64 v[166:167], s[82:83], 0, v[170:171]
	v_lshl_add_u64 v[164:165], s[14:15], 0, v[170:171]
	global_load_dwordx2 v[178:179], v[166:167], off
	v_lshl_add_u64 v[166:167], s[16:17], 0, v[170:171]
	v_lshl_add_u64 v[176:177], s[84:85], 0, v[170:171]
	v_lshl_add_u64 v[180:181], s[90:91], 0, v[170:171]
	v_lshl_add_u64 v[182:183], s[92:93], 0, v[170:171]
	v_lshl_add_u64 v[170:171], s[94:95], 0, v[170:171]
	global_load_dwordx2 v[168:169], v[166:167], off
	global_load_dwordx2 v[172:173], v[164:165], off
	v_mov_b32_e32 v200, 0
	global_load_dwordx2 v[182:183], v[182:183], off
	v_mov_b32_e32 v204, 0
	global_load_dwordx2 v[170:171], v[170:171], off
	v_mov_b32_dpp v200, v60 row_ror:1 row_mask:0xf bank_mask:0xf
	global_load_dwordx2 v[180:181], v[180:181], off
	v_mov_b32_dpp v204, v108 row_ror:1 row_mask:0xf bank_mask:0xf
	global_load_dwordx2 v[176:177], v[176:177], off
	v_mov_b32_e32 v208, 0
	v_cmp_eq_u32_e32 vcc, 1, v138
	v_readlane_b32 s13, v255, 18
	v_mov_b32_e32 v201, 0
	v_mov_b32_e32 v205, 0
	v_mov_b32_dpp v208, v100 row_ror:1 row_mask:0xf bank_mask:0xf
	v_cmp_eq_u32_e64 s[8:9], 2, v138
	v_mov_b32_dpp v201, v60 row_ror:2 row_mask:0xf bank_mask:0xf
	v_mov_b32_dpp v205, v108 row_ror:2 row_mask:0xf bank_mask:0xf
	v_mov_b32_dpp v212, v44 row_ror:1 row_mask:0xf bank_mask:0xf
	v_cmp_eq_u32_e64 s[12:13], 3, v138
	v_cmp_eq_u32_e64 s[14:15], 1, v140
	v_readlane_b32 s18, v255, 23
	v_readlane_b32 s19, v255, 24
	v_mov_b32_dpp v209, v100 row_ror:2 row_mask:0xf bank_mask:0xf
	v_cndmask_b32_e64 v187, v212, v200, s[98:99]
	v_cmp_eq_u32_e64 s[16:17], 2, v140
	v_mov_b32_dpp v202, v52 row_ror:1 row_mask:0xf bank_mask:0xf
	v_mov_b32_dpp v206, v104 row_ror:1 row_mask:0xf bank_mask:0xf
	v_mov_b32_dpp v213, v44 row_ror:2 row_mask:0xf bank_mask:0xf
	v_cmp_eq_u32_e64 s[18:19], 3, v140
	v_mov_b32_dpp v210, v96 row_ror:1 row_mask:0xf bank_mask:0xf
	v_cndmask_b32_e64 v193, v213, v201, s[100:101]
	v_mov_b32_dpp v203, v52 row_ror:2 row_mask:0xf bank_mask:0xf
	v_mov_b32_dpp v207, v104 row_ror:2 row_mask:0xf bank_mask:0xf
	v_mov_b32_dpp v214, v36 row_ror:1 row_mask:0xf bank_mask:0xf
	v_mov_b32_dpp v211, v96 row_ror:2 row_mask:0xf bank_mask:0xf
	v_cndmask_b32_e64 v186, v214, v202, s[98:99]
	v_mov_b32_dpp v215, v36 row_ror:2 row_mask:0xf bank_mask:0xf
	v_cndmask_b32_e64 v192, v215, v203, s[100:101]
	v_mov_b32_e32 v188, v52
	v_mov_b32_e32 v189, v60
	v_readlane_b32 s20, v255, 25
	v_readlane_b32 s21, v255, 26
	v_cmp_ne_u64_e64 s[20:21], 0, v[142:143]
	v_cmp_eq_u32_e64 s[22:23], 2, v142
	v_cmp_eq_u32_e64 s[24:25], 3, v142
	v_cmp_ne_u64_e64 s[52:53], 0, v[144:145]
	v_cmp_eq_u32_e64 s[54:55], 2, v144
	v_cmp_eq_u32_e64 s[56:57], 3, v144
	v_mov_b32_e32 v198, v104
	v_mov_b32_e32 v199, v108
	v_cmp_eq_u32_e64 s[40:41], 1, v146
	v_cmp_eq_u32_e64 s[42:43], 2, v146
	v_cmp_eq_u32_e64 s[44:45], 3, v146
	s_waitcnt vmcnt(0)
	v_mov_b32_e32 v185, v178
	v_cmp_eq_u32_e64 s[46:47], 1, v148
	v_cmp_eq_u32_e64 s[48:49], 2, v148
	v_cmp_eq_u32_e64 s[50:51], 3, v148
	v_readlane_b32 s26, v255, 31
	v_readlane_b32 s27, v255, 32
	v_mov_b32_e32 v191, v168
	v_cmp_eq_u32_e64 s[26:27], 1, v150
	v_cmp_eq_u32_e64 s[28:29], 2, v150
	v_mov_b32_e32 v184, v182
	v_cmp_eq_u32_e64 s[30:31], 3, v150
	v_mov_b32_e32 v190, v170
	v_pk_fma_f32 v[194:195], v[188:189], v[184:185], v[190:191]
	v_mov_b32_e32 v188, v180
	v_mov_b32_e32 v189, v174
	v_pk_fma_f32 v[194:195], v[188:189], v[186:187], v[194:195]
	v_mov_b32_e32 v186, v176
	v_mov_b32_e32 v187, v172
	v_pk_fma_f32 v[192:193], v[186:187], v[192:193], v[194:195]
	v_pk_fma_f32 v[198:199], v[198:199], v[184:185], v[190:191]
	v_mul_f32_e32 v194, 0xbfb8aa3b, v193
	v_exp_f32_e32 v194, v194
	v_cmp_eq_u32_e64 s[34:35], 1, v152
	v_cmp_eq_u32_e64 s[36:37], 2, v152
	v_cmp_eq_u32_e64 s[38:39], 3, v152
	v_add_f32_e32 v194, 1.0, v194
	v_rcp_f32_e32 v194, v194
	v_mov_b32_e32 v108, v105
	s_lshl_b32 s11, s68, 2
	v_mul_f32_e32 v193, v193, v194
	v_mul_f32_e32 v192, v192, v193
	v_cndmask_b32_e64 v195, v200, v204, s[98:99]
	v_cndmask_b32_e64 v197, v201, v205, s[100:101]
	v_cndmask_b32_e64 v194, v202, v206, s[98:99]
	v_cndmask_b32_e64 v196, v203, v207, s[100:101]
	v_pk_fma_f32 v[194:195], v[188:189], v[194:195], v[198:199]
	v_mov_b32_e32 v198, v96
	v_pk_fma_f32 v[194:195], v[186:187], v[196:197], v[194:195]
	v_mov_b32_e32 v199, v100
	v_mul_f32_e32 v104, 0xbfb8aa3b, v195
	v_exp_f32_e32 v104, v104
	v_pk_fma_f32 v[198:199], v[198:199], v[184:185], v[190:191]
	v_mov_b32_e32 v100, v97
	v_add_f32_e32 v104, 1.0, v104
	v_rcp_f32_e32 v104, v104
	s_nop 0
	v_mul_f32_e32 v104, v195, v104
	v_mul_f32_e32 v193, v194, v104
	v_cndmask_b32_e64 v195, v204, v208, s[98:99]
	v_cndmask_b32_e64 v197, v205, v209, s[100:101]
	v_cndmask_b32_e64 v194, v206, v210, s[98:99]
	v_cndmask_b32_e64 v196, v207, v211, s[100:101]
	v_pk_fma_f32 v[194:195], v[188:189], v[194:195], v[198:199]
	v_mov_b32_e32 v198, v36
	v_pk_fma_f32 v[194:195], v[186:187], v[196:197], v[194:195]
	v_mov_b32_e32 v199, v44
	v_mul_f32_e32 v96, 0xbfb8aa3b, v195
	v_exp_f32_e32 v96, v96
	v_pk_fma_f32 v[184:185], v[198:199], v[184:185], v[190:191]
; __device__ __forceinline__ unsigned cvt_pk_bf16(float lo, float hi) { unsigned r; asm volatile("v_cvt_pk_bf16_f32 %0, %1, %2" : "=v"(r) : "v"(lo), "v"(hi)); return r; }
; __device__ __forceinline__ float siluf(float x) { return x * __builtin_amdgcn_rcpf(1.f + __expf(-x)); }
;     __device__ __forceinline__ void operator()(const f32x4 (&acc)[2][2][4][2], const pg8::Unit& u, int wr, int wc, int fr, int fq) const {
;     ...
;             for (int ai = 0; ai < 2; ++ai) {
;                 float rr[4][2];
; #pragma unroll
;                 for (int ii = 0; ii < 2; ++ii) {
;                     const int c8 = 2 * cp + ii, n = c8 >> 2, i = c8 & 3;
;                     float ua[4], ub[4], r1a[4], r2a[4], r1b[4], r2b[4];
; #pragma unroll
;                     for (int m = 0; m < 4; ++m) { ua[m] = acc[ai][0][m][n][i]; ub[m] = acc[ai][1][m][n][i];
;                         r1a[m] = dpp_ror<0x121>(ua[m]); r2a[m] = dpp_ror<0x122>(ua[m]); r1b[m] = dpp_ror<0x121>(ub[m]); r2b[m] = dpp_ror<0x122>(ub[m]); }
; #pragma unroll
;                     for (int m = 0; m < 4; ++m) {
;                         const float p1a = fr >= 1 ? r1a[m] : r1a[(m + 3) & 3], p2a = fr >= 2 ? r2a[m] : r2a[(m + 3) & 3];
;                         const float p1b = fr >= 1 ? r1b[m] : r1b[(m + 3) & 3], p2b = fr >= 2 ? r2b[m] : r2b[(m + 3) & 3];
;                         const float ca = ba[ii] + wa2[ii] * ua[m] + wa1[ii] * p1a + wa0[ii] * p2a;
;                         const float cb = bb[ii] + wb2[ii] * ub[m] + wb1[ii] * p1b + wb0[ii] * p2b;
;                         rr[m][ii] = siluf(ca) * cb;
;                     }
;                 }
; #pragma unroll
;                 for (int m = 0; m < 4; ++m) outp[ai][m][cp] = pg8::cvt_pk_bf16(rr[m][0], rr[m][1]);
	v_mov_b32_e32 v190, v183
	v_add_f32_e32 v96, 1.0, v96
	v_rcp_f32_e32 v96, v96
	v_mov_b32_dpp v199, v61 row_ror:1 row_mask:0xf bank_mask:0xf
	v_mov_b32_e32 v191, v179
	v_mul_f32_e32 v96, v195, v96
	v_mul_f32_e32 v216, v194, v96
	v_cndmask_b32_e64 v195, v208, v212, s[98:99]
	v_cndmask_b32_e64 v197, v209, v213, s[100:101]
	v_cndmask_b32_e64 v194, v210, v214, s[98:99]
	v_cndmask_b32_e64 v196, v211, v215, s[100:101]
	v_pk_fma_f32 v[184:185], v[188:189], v[194:195], v[184:185]
	v_pk_fma_f32 v[184:185], v[186:187], v[196:197], v[184:185]
	v_mul_f32_e32 v96, 0xbfb8aa3b, v185
	v_exp_f32_e32 v96, v96
	v_mov_b32_dpp v203, v109 row_ror:1 row_mask:0xf bank_mask:0xf
	v_add_f32_e32 v96, 1.0, v96
	v_rcp_f32_e32 v96, v96
	v_mov_b32_dpp v207, v101 row_ror:1 row_mask:0xf bank_mask:0xf
	v_mov_b32_dpp v200, v61 row_ror:2 row_mask:0xf bank_mask:0xf
	v_mul_f32_e32 v96, v185, v96
	v_mul_f32_e32 v198, v184, v96
	v_mov_b32_dpp v204, v109 row_ror:2 row_mask:0xf bank_mask:0xf
	v_mov_b32_dpp v211, v45 row_ror:1 row_mask:0xf bank_mask:0xf
	v_mov_b32_dpp v208, v101 row_ror:2 row_mask:0xf bank_mask:0xf
	v_cndmask_b32_e64 v185, v211, v199, s[98:99]
	v_mov_b32_dpp v201, v53 row_ror:1 row_mask:0xf bank_mask:0xf
	v_mov_b32_dpp v205, v105 row_ror:1 row_mask:0xf bank_mask:0xf
	v_mov_b32_dpp v212, v45 row_ror:2 row_mask:0xf bank_mask:0xf
	v_mov_b32_dpp v209, v97 row_ror:1 row_mask:0xf bank_mask:0xf
	v_cndmask_b32_e64 v187, v212, v200, s[100:101]
	v_mov_b32_dpp v202, v53 row_ror:2 row_mask:0xf bank_mask:0xf
	v_mov_b32_dpp v206, v105 row_ror:2 row_mask:0xf bank_mask:0xf
	v_mov_b32_dpp v213, v37 row_ror:1 row_mask:0xf bank_mask:0xf
	v_mov_b32_dpp v210, v97 row_ror:2 row_mask:0xf bank_mask:0xf
	v_cndmask_b32_e64 v184, v213, v201, s[98:99]
	v_mov_b32_e32 v188, v53
	v_mov_b32_e32 v189, v61
	v_mov_b32_e32 v194, v171
	v_mov_b32_e32 v195, v169
	v_mov_b32_dpp v214, v37 row_ror:2 row_mask:0xf bank_mask:0xf
	v_pk_fma_f32 v[188:189], v[188:189], v[190:191], v[194:195]
	v_mov_b32_e32 v196, v181
	v_mov_b32_e32 v197, v175
	v_cndmask_b32_e64 v186, v214, v202, s[100:101]
	v_pk_fma_f32 v[184:185], v[196:197], v[184:185], v[188:189]
	v_mov_b32_e32 v188, v177
	v_mov_b32_e32 v189, v173
	v_pk_fma_f32 v[184:185], v[188:189], v[186:187], v[184:185]
	v_pk_fma_f32 v[104:105], v[108:109], v[190:191], v[194:195]
	v_mul_f32_e32 v96, 0xbfb8aa3b, v185
	v_exp_f32_e32 v96, v96
	s_nop 0
	v_add_f32_e32 v96, 1.0, v96
	v_rcp_f32_e32 v96, v96
	s_nop 0
	v_mul_f32_e32 v96, v185, v96
	v_mul_f32_e32 v215, v184, v96
	v_cndmask_b32_e64 v185, v199, v203, s[98:99]
	v_cndmask_b32_e64 v187, v200, v204, s[100:101]
	v_cndmask_b32_e64 v184, v201, v205, s[98:99]
	v_cndmask_b32_e64 v186, v202, v206, s[100:101]
	v_pk_fma_f32 v[104:105], v[196:197], v[184:185], v[104:105]
	v_pk_fma_f32 v[104:105], v[188:189], v[186:187], v[104:105]
	v_mul_f32_e32 v96, 0xbfb8aa3b, v105
	v_exp_f32_e32 v96, v96
	v_mov_b32_dpp v185, v124 row_ror:2 row_mask:0xf bank_mask:0xf
	v_mov_b32_dpp v186, v120 row_ror:1 row_mask:0xf bank_mask:0xf
	v_add_f32_e32 v96, 1.0, v96
	v_rcp_f32_e32 v96, v96
	v_mov_b32_dpp v187, v120 row_ror:2 row_mask:0xf bank_mask:0xf
	v_fma_f32 v120, v120, v182, v170
	v_mul_f32_e32 v96, v105, v96
	v_mul_f32_e32 v184, v104, v96
	v_cndmask_b32_e64 v105, v203, v207, s[98:99]
	v_cndmask_b32_e64 v109, v204, v208, s[100:101]
	v_cndmask_b32_e64 v104, v205, v209, s[98:99]
	v_cndmask_b32_e64 v108, v206, v210, s[100:101]
	v_pk_fma_f32 v[96:97], v[100:101], v[190:191], v[194:195]
	s_nop 0
	v_pk_fma_f32 v[96:97], v[196:197], v[104:105], v[96:97]
	v_mov_b32_e32 v104, v37
	v_pk_fma_f32 v[96:97], v[188:189], v[108:109], v[96:97]
	v_mov_b32_e32 v105, v45
	v_mul_f32_e32 v100, 0xbfb8aa3b, v97
	v_exp_f32_e32 v100, v100
	v_pk_fma_f32 v[104:105], v[104:105], v[190:191], v[194:195]
	v_cvt_pk_bf16_f32 v108, v192, v215
	v_add_f32_e32 v100, 1.0, v100
	v_rcp_f32_e32 v100, v100
	v_mov_b32_dpp v192, v12 row_ror:1 row_mask:0xf bank_mask:0xf
	v_mov_b32_e32 v190, 0
	v_mov_b32_e32 v191, 0
	v_mul_f32_e32 v97, v97, v100
	v_mul_f32_e32 v109, v96, v97
	v_cndmask_b32_e64 v97, v207, v211, s[98:99]
	v_cndmask_b32_e64 v101, v208, v212, s[100:101]
	v_cndmask_b32_e64 v96, v209, v213, s[98:99]
	v_cndmask_b32_e64 v100, v210, v214, s[100:101]
	v_pk_fma_f32 v[96:97], v[196:197], v[96:97], v[104:105]
	v_cvt_pk_bf16_f32 v104, v193, v184
	v_pk_fma_f32 v[96:97], v[188:189], v[100:101], v[96:97]
	v_mul_f32_e32 v100, 0xbfb8aa3b, v97
	v_exp_f32_e32 v100, v100
	v_mov_b32_dpp v184, v124 row_ror:1 row_mask:0xf bank_mask:0xf
	v_mov_b32_dpp v101, v28 row_ror:2 row_mask:0xf bank_mask:0xf
	v_add_f32_e32 v100, 1.0, v100
	v_rcp_f32_e32 v100, v100
	v_mov_b32_dpp v188, v116 row_ror:1 row_mask:0xf bank_mask:0xf
	v_mul_f32_e32 v97, v97, v100
	v_mul_f32_e32 v96, v96, v97
	v_mov_b32_dpp v189, v116 row_ror:2 row_mask:0xf bank_mask:0xf
	v_mov_b32_dpp v97, v28 row_ror:1 row_mask:0xf bank_mask:0xf
	v_mov_b32_dpp v193, v12 row_ror:2 row_mask:0xf bank_mask:0xf
	v_cndmask_b32_e64 v196, v192, v97, s[98:99]
	v_fma_f32 v200, v28, v178, v168
	v_cndmask_b32_e64 v197, v193, v101, s[100:101]
	v_fmac_f32_e32 v200, v174, v196
	v_fmac_f32_e32 v200, v172, v197
	v_mul_f32_e32 v197, 0xbfb8aa3b, v200
	v_exp_f32_e32 v197, v197
	v_cvt_pk_bf16_f32 v100, v216, v109
	v_add_f32_e32 v197, 1.0, v197
	v_mov_b32_dpp v105, v20 row_ror:1 row_mask:0xf bank_mask:0xf
	v_cvt_pk_bf16_f32 v96, v198, v96
	v_mov_b32_dpp v109, v20 row_ror:2 row_mask:0xf bank_mask:0xf
	v_mov_b32_dpp v190, v112 row_ror:1 row_mask:0xf bank_mask:0xf
	v_rcp_f32_e32 v197, v197
	v_mov_b32_dpp v191, v112 row_ror:2 row_mask:0xf bank_mask:0xf
	v_mov_b32_dpp v194, v4 row_ror:1 row_mask:0xf bank_mask:0xf
	v_mov_b32_dpp v195, v4 row_ror:2 row_mask:0xf bank_mask:0xf
; __device__ __forceinline__ unsigned cvt_pk_bf16(float lo, float hi) { unsigned r; asm volatile("v_cvt_pk_bf16_f32 %0, %1, %2" : "=v"(r) : "v"(lo), "v"(hi)); return r; }
; __device__ __forceinline__ float siluf(float x) { return x * __builtin_amdgcn_rcpf(1.f + __expf(-x)); }
;     __device__ __forceinline__ void operator()(const f32x4 (&acc)[2][2][4][2], const pg8::Unit& u, int wr, int wc, int fr, int fq) const {
;     ...
;             for (int ai = 0; ai < 2; ++ai) {
;                 float rr[4][2];
; #pragma unroll
;                 for (int ii = 0; ii < 2; ++ii) {
;                     const int c8 = 2 * cp + ii, n = c8 >> 2, i = c8 & 3;
;                     float ua[4], ub[4], r1a[4], r2a[4], r1b[4], r2b[4];
; #pragma unroll
;                     for (int m = 0; m < 4; ++m) { ua[m] = acc[ai][0][m][n][i]; ub[m] = acc[ai][1][m][n][i];
;                         r1a[m] = dpp_ror<0x121>(ua[m]); r2a[m] = dpp_ror<0x122>(ua[m]); r1b[m] = dpp_ror<0x121>(ub[m]); r2b[m] = dpp_ror<0x122>(ub[m]); }
; #pragma unroll
;                     for (int m = 0; m < 4; ++m) {
;                         const float p1a = fr >= 1 ? r1a[m] : r1a[(m + 3) & 3], p2a = fr >= 2 ? r2a[m] : r2a[(m + 3) & 3];
;                         const float p1b = fr >= 1 ? r1b[m] : r1b[(m + 3) & 3], p2b = fr >= 2 ? r2b[m] : r2b[(m + 3) & 3];
;                         const float ca = ba[ii] + wa2[ii] * ua[m] + wa1[ii] * p1a + wa0[ii] * p2a;
;                         const float cb = bb[ii] + wb2[ii] * ub[m] + wb1[ii] * p1b + wb0[ii] * p2b;
;                         rr[m][ii] = siluf(ca) * cb;
;                     }
;                 }
; #pragma unroll
;                 for (int m = 0; m < 4; ++m) outp[ai][m][cp] = pg8::cvt_pk_bf16(rr[m][0], rr[m][1]);
	v_cndmask_b32_e64 v198, v194, v105, s[98:99]
	v_fma_f32 v196, v20, v182, v170
	v_cndmask_b32_e64 v199, v195, v109, s[100:101]
	v_fmac_f32_e32 v196, v180, v198
	v_fmac_f32_e32 v196, v176, v199
	v_mul_f32_e32 v197, v200, v197
	v_mul_f32_e32 v196, v196, v197
	v_cndmask_b32_e64 v197, v97, v184, s[98:99]
	v_fma_f32 v124, v124, v178, v168
	v_cndmask_b32_e64 v198, v101, v185, s[100:101]
	v_fmac_f32_e32 v124, v174, v197
	v_fmac_f32_e32 v124, v172, v198
	v_mul_f32_e32 v197, 0xbfb8aa3b, v124
	v_exp_f32_e32 v197, v197
	s_nop 0
	v_add_f32_e32 v197, 1.0, v197
	v_rcp_f32_e32 v197, v197
	v_cndmask_b32_e64 v199, v105, v186, s[98:99]
	v_cndmask_b32_e64 v200, v109, v187, s[100:101]
	v_fmac_f32_e32 v120, v180, v199
	v_fmac_f32_e32 v120, v176, v200
	v_mul_f32_e32 v124, v124, v197
	v_mul_f32_e32 v120, v120, v124
	v_cndmask_b32_e64 v124, v184, v188, s[98:99]
	v_fma_f32 v116, v116, v178, v168
	v_cndmask_b32_e64 v197, v185, v189, s[100:101]
	v_fmac_f32_e32 v116, v174, v124
	v_fmac_f32_e32 v116, v172, v197
	v_mul_f32_e32 v124, 0xbfb8aa3b, v116
	v_exp_f32_e32 v124, v124
	s_nop 0
	v_add_f32_e32 v124, 1.0, v124
	v_rcp_f32_e32 v124, v124
	v_cndmask_b32_e64 v198, v186, v190, s[98:99]
	v_fma_f32 v112, v112, v182, v170
	v_cndmask_b32_e64 v199, v187, v191, s[100:101]
	v_fmac_f32_e32 v112, v180, v198
	v_fmac_f32_e32 v112, v176, v199
	v_mul_f32_e32 v116, v116, v124
	v_mul_f32_e32 v112, v112, v116
	v_cndmask_b32_e64 v97, v188, v192, s[98:99]
	v_fma_f32 v116, v12, v178, v168
	v_cndmask_b32_e64 v101, v189, v193, s[100:101]
	v_fmac_f32_e32 v116, v174, v97
	v_fmac_f32_e32 v116, v172, v101
	v_mul_f32_e32 v101, 0xbfb8aa3b, v116
	v_exp_f32_e32 v101, v101
	s_nop 0
	v_add_f32_e32 v101, 1.0, v101
	v_rcp_f32_e32 v101, v101
	v_cndmask_b32_e64 v105, v190, v194, s[98:99]
	v_fma_f32 v97, v4, v182, v170
	v_cndmask_b32_e64 v109, v191, v195, s[100:101]
	v_fmac_f32_e32 v97, v180, v105
	v_fmac_f32_e32 v97, v176, v109
	v_mul_f32_e32 v101, v116, v101
	v_mul_f32_e32 v97, v97, v101
	s_nop 0
	v_mov_b32_dpp v101, v29 row_ror:1 row_mask:0xf bank_mask:0xf
	v_mov_b32_dpp v124, v125 row_ror:1 row_mask:0xf bank_mask:0xf
	v_mov_b32_dpp v105, v29 row_ror:2 row_mask:0xf bank_mask:0xf
	v_mov_b32_dpp v168, v125 row_ror:2 row_mask:0xf bank_mask:0xf
	v_mov_b32_dpp v174, v117 row_ror:1 row_mask:0xf bank_mask:0xf
	v_mov_b32_dpp v176, v117 row_ror:2 row_mask:0xf bank_mask:0xf
	v_mov_b32_dpp v182, v13 row_ror:1 row_mask:0xf bank_mask:0xf
	v_mov_b32_dpp v184, v13 row_ror:2 row_mask:0xf bank_mask:0xf
	v_cndmask_b32_e64 v187, v182, v101, s[98:99]
	v_fma_f32 v191, v29, v179, v169
	v_cndmask_b32_e64 v188, v184, v105, s[100:101]
	v_fmac_f32_e32 v191, v175, v187
	v_fmac_f32_e32 v191, v173, v188
	v_mul_f32_e32 v188, 0xbfb8aa3b, v191
	v_exp_f32_e32 v188, v188
	v_mov_b32_dpp v109, v21 row_ror:1 row_mask:0xf bank_mask:0xf
	v_mov_b32_dpp v170, v121 row_ror:1 row_mask:0xf bank_mask:0xf
	v_add_f32_e32 v188, 1.0, v188
	v_mov_b32_dpp v116, v21 row_ror:2 row_mask:0xf bank_mask:0xf
	v_mov_b32_dpp v172, v121 row_ror:2 row_mask:0xf bank_mask:0xf
	v_mov_b32_dpp v178, v113 row_ror:1 row_mask:0xf bank_mask:0xf
	v_rcp_f32_e32 v188, v188
	v_mov_b32_dpp v180, v113 row_ror:2 row_mask:0xf bank_mask:0xf
	v_mov_b32_dpp v185, v5 row_ror:1 row_mask:0xf bank_mask:0xf
	v_mov_b32_dpp v186, v5 row_ror:2 row_mask:0xf bank_mask:0xf
	v_cndmask_b32_e64 v189, v185, v109, s[98:99]
	v_fma_f32 v187, v21, v183, v171
	v_cndmask_b32_e64 v190, v186, v116, s[100:101]
	v_fmac_f32_e32 v187, v181, v189
	v_fmac_f32_e32 v187, v177, v190
	v_mul_f32_e32 v188, v191, v188
	v_mul_f32_e32 v187, v187, v188
	v_cndmask_b32_e64 v188, v101, v124, s[98:99]
	v_fma_f32 v125, v125, v179, v169
	v_cndmask_b32_e64 v189, v105, v168, s[100:101]
	v_fmac_f32_e32 v125, v175, v188
	v_fmac_f32_e32 v125, v173, v189
	v_mul_f32_e32 v188, 0xbfb8aa3b, v125
	v_exp_f32_e32 v188, v188
	s_nop 0
	v_add_f32_e32 v188, 1.0, v188
	v_rcp_f32_e32 v188, v188
	v_cndmask_b32_e64 v190, v109, v170, s[98:99]
	v_fma_f32 v121, v121, v183, v171
	v_cndmask_b32_e64 v191, v116, v172, s[100:101]
	v_fmac_f32_e32 v121, v181, v190
	v_fmac_f32_e32 v121, v177, v191
	v_mul_f32_e32 v125, v125, v188
	v_mul_f32_e32 v121, v121, v125
	v_fma_f32 v117, v117, v179, v169
	v_cndmask_b32_e64 v101, v174, v182, s[98:99]
	v_fmac_f32_e32 v169, v13, v179
	v_cndmask_b32_e64 v105, v176, v184, s[100:101]
	v_fmac_f32_e32 v169, v175, v101
	v_cndmask_b32_e64 v125, v124, v174, s[98:99]
	v_fmac_f32_e32 v169, v173, v105
	v_cndmask_b32_e64 v188, v168, v176, s[100:101]
	v_fmac_f32_e32 v117, v175, v125
	v_mul_f32_e32 v101, 0xbfb8aa3b, v169
	v_fmac_f32_e32 v117, v173, v188
	v_exp_f32_e32 v101, v101
	v_mul_f32_e32 v125, 0xbfb8aa3b, v117
	v_exp_f32_e32 v125, v125
	v_add_f32_e32 v101, 1.0, v101
	v_rcp_f32_e32 v101, v101
	v_add_f32_e32 v125, 1.0, v125
	v_fma_f32 v113, v113, v183, v171
	v_rcp_f32_e32 v125, v125
	v_cndmask_b32_e64 v109, v178, v185, s[98:99]
	v_fmac_f32_e32 v171, v5, v183
	v_cndmask_b32_e64 v116, v180, v186, s[100:101]
	v_fmac_f32_e32 v171, v181, v109
	v_or_b32_e32 v168, 2, v162
	v_cndmask_b32_e64 v189, v170, v178, s[98:99]
	v_fmac_f32_e32 v171, v177, v116
	v_mul_f32_e32 v101, v169, v101
	v_ashrrev_i32_e32 v169, 31, v168
	v_cndmask_b32_e64 v190, v172, v180, s[100:101]
	v_fmac_f32_e32 v113, v181, v189
	v_mul_f32_e32 v101, v171, v101
	v_lshlrev_b64 v[170:171], 2, v[168:169]
	v_fmac_f32_e32 v113, v177, v190
	v_mul_f32_e32 v117, v117, v125
	v_lshl_add_u64 v[168:169], s[80:81], 0, v[170:171]
	v_mul_f32_e32 v113, v113, v117
	v_cvt_pk_bf16_f32 v124, v196, v187
	v_cvt_pk_bf16_f32 v120, v120, v121
	v_cvt_pk_bf16_f32 v116, v112, v113
	v_cvt_pk_bf16_f32 v112, v97, v101
	global_load_dwordx2 v[174:175], v[168:169], off
	v_lshl_add_u64 v[168:169], s[82:83], 0, v[170:171]
; __device__ __forceinline__ unsigned cvt_pk_bf16(float lo, float hi) { unsigned r; asm volatile("v_cvt_pk_bf16_f32 %0, %1, %2" : "=v"(r) : "v"(lo), "v"(hi)); return r; }
; __device__ __forceinline__ float siluf(float x) { return x * __builtin_amdgcn_rcpf(1.f + __expf(-x)); }
;     __device__ __forceinline__ void operator()(const f32x4 (&acc)[2][2][4][2], const pg8::Unit& u, int wr, int wc, int fr, int fq) const {
;     ...
;             const int chp = ch0 + 2 * cp;
;             const f32x2 wa0 = *(const f32x2*)(wconv + chp), wa1 = *(const f32x2*)(wconv + NUP + chp), wa2 = *(const f32x2*)(wconv + 2 * NUP + chp), ba = *(const f32x2*)(bconv + chp);
;             const f32x2 wb0 = *(const f32x2*)(wconv + DFF + chp), wb1 = *(const f32x2*)(wconv + NUP + DFF + chp), wb2 = *(const f32x2*)(wconv + 2 * NUP + DFF + chp), bb = *(const f32x2*)(bconv + DFF + chp);
; #pragma unroll
;             for (int ai = 0; ai < 2; ++ai) {
;                 float rr[4][2];
; #pragma unroll
;                 for (int ii = 0; ii < 2; ++ii) {
;                     const int c8 = 2 * cp + ii, n = c8 >> 2, i = c8 & 3;
;                     float ua[4], ub[4], r1a[4], r2a[4], r1b[4], r2b[4];
; #pragma unroll
;                     for (int m = 0; m < 4; ++m) { ua[m] = acc[ai][0][m][n][i]; ub[m] = acc[ai][1][m][n][i];
;                         r1a[m] = dpp_ror<0x121>(ua[m]); r2a[m] = dpp_ror<0x122>(ua[m]); r1b[m] = dpp_ror<0x121>(ub[m]); r2b[m] = dpp_ror<0x122>(ub[m]); }
; #pragma unroll
;                     for (int m = 0; m < 4; ++m) {
;                         const float p1a = fr >= 1 ? r1a[m] : r1a[(m + 3) & 3], p2a = fr >= 2 ? r2a[m] : r2a[(m + 3) & 3];
;                         const float p1b = fr >= 1 ? r1b[m] : r1b[(m + 3) & 3], p2b = fr >= 2 ? r2b[m] : r2b[(m + 3) & 3];
;                         const float ca = ba[ii] + wa2[ii] * ua[m] + wa1[ii] * p1a + wa0[ii] * p2a;
;                         const float cb = bb[ii] + wb2[ii] * ub[m] + wb1[ii] * p1b + wb0[ii] * p2b;
;                         rr[m][ii] = siluf(ca) * cb;
;                     }
;                 }
; #pragma unroll
;                 for (int m = 0; m < 4; ++m) outp[ai][m][cp] = pg8::cvt_pk_bf16(rr[m][0], rr[m][1]);
	v_lshl_add_u64 v[176:177], s[84:85], 0, v[170:171]
	v_lshl_add_u64 v[178:179], s[90:91], 0, v[170:171]
	v_lshl_add_u64 v[182:183], s[92:93], 0, v[170:171]
	v_lshl_add_u64 v[170:171], s[94:95], 0, v[170:171]
	global_load_dwordx2 v[172:173], v[164:165], off offset:8
	global_load_dwordx2 v[180:181], v[168:169], off
	s_nop 0
	global_load_dwordx2 v[168:169], v[166:167], off offset:8
	global_load_dwordx2 v[182:183], v[182:183], off
	global_load_dwordx2 v[170:171], v[170:171], off
	v_mov_b32_dpp v97, v62 row_ror:1 row_mask:0xf bank_mask:0xf
	global_load_dwordx2 v[178:179], v[178:179], off
	v_mov_b32_dpp v113, v110 row_ror:1 row_mask:0xf bank_mask:0xf
	global_load_dwordx2 v[176:177], v[176:177], off
	v_mov_b32_dpp v198, v102 row_ror:1 row_mask:0xf bank_mask:0xf
	v_mov_b32_dpp v101, v62 row_ror:2 row_mask:0xf bank_mask:0xf
	v_mov_b32_dpp v117, v110 row_ror:2 row_mask:0xf bank_mask:0xf
	v_mov_b32_dpp v202, v46 row_ror:1 row_mask:0xf bank_mask:0xf
	v_mov_b32_dpp v199, v102 row_ror:2 row_mask:0xf bank_mask:0xf
	v_cndmask_b32_e64 v185, v202, v97, s[98:99]
	v_mov_b32_dpp v105, v54 row_ror:1 row_mask:0xf bank_mask:0xf
	v_mov_b32_dpp v121, v106 row_ror:1 row_mask:0xf bank_mask:0xf
	v_mov_b32_dpp v203, v46 row_ror:2 row_mask:0xf bank_mask:0xf
	v_mov_b32_dpp v109, v54 row_ror:2 row_mask:0xf bank_mask:0xf
	v_mov_b32_dpp v125, v106 row_ror:2 row_mask:0xf bank_mask:0xf
	v_mov_b32_dpp v200, v98 row_ror:1 row_mask:0xf bank_mask:0xf
	v_cndmask_b32_e64 v187, v203, v101, s[100:101]
	v_mov_b32_dpp v201, v98 row_ror:2 row_mask:0xf bank_mask:0xf
	v_mov_b32_dpp v204, v38 row_ror:1 row_mask:0xf bank_mask:0xf
	v_mov_b32_e32 v188, v54
	v_mov_b32_e32 v189, v62
	v_mov_b32_dpp v205, v38 row_ror:2 row_mask:0xf bank_mask:0xf
	v_cndmask_b32_e64 v184, v204, v105, s[98:99]
	v_cndmask_b32_e64 v186, v205, v109, s[100:101]
	v_mov_b32_e32 v196, v106
	v_mov_b32_e32 v197, v110
	v_mov_b32_e32 v110, v107
	s_waitcnt vmcnt(7)
	v_mov_b32_e32 v195, v174
	s_waitcnt vmcnt(5)
	v_mov_b32_e32 v191, v180
	s_waitcnt vmcnt(4)
	v_mov_b32_e32 v193, v168
	s_waitcnt vmcnt(3)
	v_mov_b32_e32 v190, v182
	s_waitcnt vmcnt(2)
	v_mov_b32_e32 v192, v170
	v_pk_fma_f32 v[188:189], v[188:189], v[190:191], v[192:193]
	s_waitcnt vmcnt(1)
	v_mov_b32_e32 v194, v178
	v_pk_fma_f32 v[184:185], v[194:195], v[184:185], v[188:189]
	s_waitcnt vmcnt(0)
	v_mov_b32_e32 v188, v176
	v_mov_b32_e32 v189, v172
	v_pk_fma_f32 v[184:185], v[188:189], v[186:187], v[184:185]
	v_pk_fma_f32 v[196:197], v[196:197], v[190:191], v[192:193]
	v_mul_f32_e32 v186, 0xbfb8aa3b, v185
	v_exp_f32_e32 v186, v186
	s_nop 0
	v_add_f32_e32 v186, 1.0, v186
	v_rcp_f32_e32 v186, v186
	s_nop 0
	v_mul_f32_e32 v185, v185, v186
	v_mul_f32_e32 v206, v184, v185
	v_cndmask_b32_e64 v185, v97, v113, s[98:99]
	v_cndmask_b32_e64 v187, v101, v117, s[100:101]
	v_cndmask_b32_e64 v184, v105, v121, s[98:99]
	v_cndmask_b32_e64 v186, v109, v125, s[100:101]
	v_pk_fma_f32 v[184:185], v[194:195], v[184:185], v[196:197]
	v_mov_b32_e32 v196, v98
	v_pk_fma_f32 v[184:185], v[188:189], v[186:187], v[184:185]
	v_mov_b32_e32 v197, v102
	v_mul_f32_e32 v106, 0xbfb8aa3b, v185
	v_exp_f32_e32 v106, v106
	v_pk_fma_f32 v[196:197], v[196:197], v[190:191], v[192:193]
	v_mov_b32_e32 v102, v99
	v_add_f32_e32 v106, 1.0, v106
	v_rcp_f32_e32 v106, v106
	s_nop 0
	v_mul_f32_e32 v106, v185, v106
	v_mul_f32_e32 v207, v184, v106
	v_cndmask_b32_e64 v185, v113, v198, s[98:99]
	v_cndmask_b32_e64 v187, v117, v199, s[100:101]
	v_cndmask_b32_e64 v184, v121, v200, s[98:99]
	v_cndmask_b32_e64 v186, v125, v201, s[100:101]
	v_pk_fma_f32 v[184:185], v[194:195], v[184:185], v[196:197]
	v_cndmask_b32_e64 v97, v97, v113, s[26:27]
	v_pk_fma_f32 v[184:185], v[188:189], v[186:187], v[184:185]
	v_cndmask_b32_e64 v97, v97, v198, s[28:29]
	v_mul_f32_e32 v98, 0xbfb8aa3b, v185
	v_exp_f32_e32 v98, v98
	v_mov_b32_e32 v196, v38
	v_mov_b32_e32 v197, v46
	v_pk_fma_f32 v[190:191], v[196:197], v[190:191], v[192:193]
	v_add_f32_e32 v98, 1.0, v98
	v_rcp_f32_e32 v98, v98
	s_nop 0
	v_mul_f32_e32 v98, v185, v98
	v_cndmask_b32_e64 v185, v97, v202, s[30:31]
	v_cndmask_b32_e64 v187, v199, v203, s[100:101]
	v_mul_f32_e32 v208, v184, v98
	v_cndmask_b32_e64 v184, v200, v204, s[98:99]
	v_cndmask_b32_e64 v186, v201, v205, s[100:101]
	v_pk_fma_f32 v[184:185], v[194:195], v[184:185], v[190:191]
	v_pk_fma_f32 v[184:185], v[188:189], v[186:187], v[184:185]
	v_mul_f32_e32 v97, 0xbfb8aa3b, v185
	v_exp_f32_e32 v97, v97
	v_mov_b32_dpp v101, v63 row_ror:1 row_mask:0xf bank_mask:0xf
	v_mov_b32_dpp v117, v111 row_ror:1 row_mask:0xf bank_mask:0xf
	v_add_f32_e32 v97, 1.0, v97
	v_rcp_f32_e32 v97, v97
	v_mov_b32_dpp v197, v103 row_ror:1 row_mask:0xf bank_mask:0xf
	v_mov_b32_dpp v105, v63 row_ror:2 row_mask:0xf bank_mask:0xf
	v_mov_b32_dpp v121, v111 row_ror:2 row_mask:0xf bank_mask:0xf
	v_mov_b32_dpp v201, v47 row_ror:1 row_mask:0xf bank_mask:0xf
	v_mul_f32_e32 v97, v185, v97
	v_mov_b32_dpp v198, v103 row_ror:2 row_mask:0xf bank_mask:0xf
	v_cndmask_b32_e64 v185, v201, v101, s[98:99]
	v_mov_b32_dpp v109, v55 row_ror:1 row_mask:0xf bank_mask:0xf
	v_mov_b32_dpp v125, v107 row_ror:1 row_mask:0xf bank_mask:0xf
	v_mov_b32_dpp v202, v47 row_ror:2 row_mask:0xf bank_mask:0xf
	v_mov_b32_dpp v199, v99 row_ror:1 row_mask:0xf bank_mask:0xf
	v_cndmask_b32_e64 v187, v202, v105, s[100:101]
	v_mov_b32_dpp v113, v55 row_ror:2 row_mask:0xf bank_mask:0xf
	v_mov_b32_dpp v196, v107 row_ror:2 row_mask:0xf bank_mask:0xf
	v_mov_b32_dpp v203, v39 row_ror:1 row_mask:0xf bank_mask:0xf
	v_mul_f32_e32 v97, v184, v97
	v_mov_b32_dpp v200, v99 row_ror:2 row_mask:0xf bank_mask:0xf
	v_cndmask_b32_e64 v184, v203, v109, s[98:99]
	v_mov_b32_e32 v188, v55
	v_mov_b32_e32 v189, v63
; __device__ __forceinline__ unsigned cvt_pk_bf16(float lo, float hi) { unsigned r; asm volatile("v_cvt_pk_bf16_f32 %0, %1, %2" : "=v"(r) : "v"(lo), "v"(hi)); return r; }
; __device__ __forceinline__ float siluf(float x) { return x * __builtin_amdgcn_rcpf(1.f + __expf(-x)); }
;     __device__ __forceinline__ void operator()(const f32x4 (&acc)[2][2][4][2], const pg8::Unit& u, int wr, int wc, int fr, int fq) const {
;     ...
;             for (int ai = 0; ai < 2; ++ai) {
;                 float rr[4][2];
; #pragma unroll
;                 for (int ii = 0; ii < 2; ++ii) {
;                     const int c8 = 2 * cp + ii, n = c8 >> 2, i = c8 & 3;
;                     float ua[4], ub[4], r1a[4], r2a[4], r1b[4], r2b[4];
; #pragma unroll
;                     for (int m = 0; m < 4; ++m) { ua[m] = acc[ai][0][m][n][i]; ub[m] = acc[ai][1][m][n][i];
;                         r1a[m] = dpp_ror<0x121>(ua[m]); r2a[m] = dpp_ror<0x122>(ua[m]); r1b[m] = dpp_ror<0x121>(ub[m]); r2b[m] = dpp_ror<0x122>(ub[m]); }
; #pragma unroll
;                     for (int m = 0; m < 4; ++m) {
;                         const float p1a = fr >= 1 ? r1a[m] : r1a[(m + 3) & 3], p2a = fr >= 2 ? r2a[m] : r2a[(m + 3) & 3];
;                         const float p1b = fr >= 1 ? r1b[m] : r1b[(m + 3) & 3], p2b = fr >= 2 ? r2b[m] : r2b[(m + 3) & 3];
;                         const float ca = ba[ii] + wa2[ii] * ua[m] + wa1[ii] * p1a + wa0[ii] * p2a;
;                         const float cb = bb[ii] + wb2[ii] * ub[m] + wb1[ii] * p1b + wb0[ii] * p2b;
;                         rr[m][ii] = siluf(ca) * cb;
;                     }
;                 }
; #pragma unroll
;                 for (int m = 0; m < 4; ++m) outp[ai][m][cp] = pg8::cvt_pk_bf16(rr[m][0], rr[m][1]);
	v_mov_b32_e32 v190, v183
	v_mov_b32_e32 v191, v181
	v_mov_b32_e32 v192, v171
	v_mov_b32_e32 v193, v169
	v_mov_b32_dpp v204, v39 row_ror:2 row_mask:0xf bank_mask:0xf
	v_pk_fma_f32 v[188:189], v[188:189], v[190:191], v[192:193]
	v_mov_b32_e32 v194, v179
	v_mov_b32_e32 v195, v175
	v_cndmask_b32_e64 v186, v204, v113, s[100:101]
	v_pk_fma_f32 v[184:185], v[194:195], v[184:185], v[188:189]
	v_mov_b32_e32 v188, v177
	v_mov_b32_e32 v189, v173
	v_pk_fma_f32 v[184:185], v[188:189], v[186:187], v[184:185]
	v_pk_fma_f32 v[106:107], v[110:111], v[190:191], v[192:193]
	v_mul_f32_e32 v98, 0xbfb8aa3b, v185
	v_exp_f32_e32 v98, v98
	s_nop 0
	v_add_f32_e32 v98, 1.0, v98
	v_rcp_f32_e32 v98, v98
	s_nop 0
	v_mul_f32_e32 v98, v185, v98
	v_mul_f32_e32 v205, v184, v98
	v_cndmask_b32_e64 v185, v101, v117, s[98:99]
	v_cndmask_b32_e64 v187, v105, v121, s[100:101]
	v_cndmask_b32_e64 v184, v109, v125, s[98:99]
	v_cndmask_b32_e64 v186, v113, v196, s[100:101]
	v_pk_fma_f32 v[106:107], v[194:195], v[184:185], v[106:107]
	v_pk_fma_f32 v[106:107], v[188:189], v[186:187], v[106:107]
	v_mul_f32_e32 v98, 0xbfb8aa3b, v107
	v_exp_f32_e32 v98, v98
	v_mov_b32_dpp v185, v14 row_ror:2 row_mask:0xf bank_mask:0xf
	v_mov_b32_dpp v186, v6 row_ror:1 row_mask:0xf bank_mask:0xf
	v_add_f32_e32 v98, 1.0, v98
	v_rcp_f32_e32 v98, v98
	v_mov_b32_dpp v187, v6 row_ror:2 row_mask:0xf bank_mask:0xf
	v_mul_f32_e32 v98, v107, v98
	v_mul_f32_e32 v184, v106, v98
	v_cndmask_b32_e64 v107, v117, v197, s[98:99]
	v_cndmask_b32_e64 v111, v121, v198, s[100:101]
	v_cndmask_b32_e64 v106, v125, v199, s[98:99]
	v_cndmask_b32_e64 v110, v196, v200, s[100:101]
	v_pk_fma_f32 v[98:99], v[102:103], v[190:191], v[192:193]
	s_nop 0
	v_pk_fma_f32 v[98:99], v[194:195], v[106:107], v[98:99]
	v_mov_b32_e32 v106, v39
	v_pk_fma_f32 v[98:99], v[188:189], v[110:111], v[98:99]
	v_mov_b32_e32 v107, v47
	v_mul_f32_e32 v102, 0xbfb8aa3b, v99
	v_exp_f32_e32 v102, v102
	v_pk_fma_f32 v[106:107], v[106:107], v[190:191], v[192:193]
	v_fma_f32 v192, v30, v180, v168
	v_add_f32_e32 v102, 1.0, v102
	v_rcp_f32_e32 v102, v102
	v_mov_b32_dpp v111, v122 row_ror:2 row_mask:0xf bank_mask:0xf
	v_mov_b32_e32 v193, 0
	v_mul_f32_e32 v99, v99, v102
	v_mul_f32_e32 v110, v98, v99
	v_cndmask_b32_e64 v99, v197, v201, s[98:99]
	v_cndmask_b32_e64 v103, v198, v202, s[100:101]
	v_cndmask_b32_e64 v98, v199, v203, s[98:99]
	v_cndmask_b32_e64 v102, v200, v204, s[100:101]
	v_pk_fma_f32 v[98:99], v[194:195], v[98:99], v[106:107]
	v_cvt_pk_bf16_f32 v109, v206, v205
	v_cvt_pk_bf16_f32 v105, v207, v184
	v_pk_fma_f32 v[98:99], v[188:189], v[102:103], v[98:99]
	v_mul_f32_e32 v101, 0xbfb8aa3b, v99
	v_exp_f32_e32 v101, v101
	v_mov_b32_dpp v106, v126 row_ror:1 row_mask:0xf bank_mask:0xf
	v_mov_b32_dpp v107, v126 row_ror:2 row_mask:0xf bank_mask:0xf
	v_add_f32_e32 v101, 1.0, v101
	v_rcp_f32_e32 v101, v101
	v_mov_b32_dpp v113, v118 row_ror:1 row_mask:0xf bank_mask:0xf
	v_mul_f32_e32 v99, v99, v101
	v_mul_f32_e32 v98, v98, v99
	v_cvt_pk_bf16_f32 v101, v208, v110
	v_cvt_pk_bf16_f32 v97, v97, v98
	v_mov_b32_dpp v117, v118 row_ror:2 row_mask:0xf bank_mask:0xf
	v_mov_b32_dpp v98, v30 row_ror:1 row_mask:0xf bank_mask:0xf
	v_mov_b32_dpp v99, v30 row_ror:2 row_mask:0xf bank_mask:0xf
	v_mov_b32_dpp v184, v14 row_ror:1 row_mask:0xf bank_mask:0xf
	v_cndmask_b32_e64 v188, v184, v98, s[98:99]
	v_cndmask_b32_e64 v189, v185, v99, s[100:101]
	v_fmac_f32_e32 v192, v174, v188
	v_fmac_f32_e32 v192, v172, v189
	v_mul_f32_e32 v189, 0xbfb8aa3b, v192
	v_exp_f32_e32 v189, v189
	v_mov_b32_dpp v102, v22 row_ror:1 row_mask:0xf bank_mask:0xf
	v_mov_b32_dpp v110, v122 row_ror:1 row_mask:0xf bank_mask:0xf
	v_add_f32_e32 v189, 1.0, v189
	v_mov_b32_dpp v103, v22 row_ror:2 row_mask:0xf bank_mask:0xf
	v_mov_b32_dpp v121, v114 row_ror:1 row_mask:0xf bank_mask:0xf
	v_rcp_f32_e32 v189, v189
	v_mov_b32_dpp v125, v114 row_ror:2 row_mask:0xf bank_mask:0xf
	v_cndmask_b32_e64 v190, v186, v102, s[98:99]
	v_fma_f32 v188, v22, v182, v170
	v_cndmask_b32_e64 v191, v187, v103, s[100:101]
	v_fmac_f32_e32 v188, v178, v190
	v_fmac_f32_e32 v188, v176, v191
	v_mul_f32_e32 v189, v192, v189
	v_mul_f32_e32 v188, v188, v189
	v_cndmask_b32_e64 v189, v98, v106, s[98:99]
	v_fma_f32 v126, v126, v180, v168
	v_cndmask_b32_e64 v190, v99, v107, s[100:101]
	v_fmac_f32_e32 v126, v174, v189
	v_fmac_f32_e32 v126, v172, v190
	v_mul_f32_e32 v189, 0xbfb8aa3b, v126
	v_exp_f32_e32 v189, v189
	s_nop 0
	v_add_f32_e32 v189, 1.0, v189
	v_rcp_f32_e32 v189, v189
	v_cndmask_b32_e64 v191, v102, v110, s[98:99]
	v_fma_f32 v122, v122, v182, v170
	v_cndmask_b32_e64 v192, v103, v111, s[100:101]
	v_fmac_f32_e32 v122, v178, v191
	v_fmac_f32_e32 v122, v176, v192
	v_mul_f32_e32 v126, v126, v189
	v_mul_f32_e32 v122, v122, v126
	v_cndmask_b32_e64 v126, v98, v106, s[40:41]
	v_cndmask_b32_e64 v98, v113, v184, s[98:99]
	v_fma_f32 v106, v14, v180, v168
	v_cndmask_b32_e64 v126, v126, v113, s[42:43]
	v_cndmask_b32_e64 v99, v117, v185, s[100:101]
	v_fmac_f32_e32 v106, v174, v98
	v_cndmask_b32_e64 v126, v126, v184, s[44:45]
	v_fma_f32 v118, v118, v180, v168
	v_fmac_f32_e32 v106, v172, v99
	v_cndmask_b32_e64 v189, v107, v117, s[100:101]
	v_fmac_f32_e32 v118, v174, v126
	v_mul_f32_e32 v99, 0xbfb8aa3b, v106
	v_fmac_f32_e32 v118, v172, v189
	v_exp_f32_e32 v99, v99
	v_mul_f32_e32 v126, 0xbfb8aa3b, v118
	v_exp_f32_e32 v126, v126
	v_add_f32_e32 v99, 1.0, v99
	v_rcp_f32_e32 v99, v99
	v_add_f32_e32 v126, 1.0, v126
	v_rcp_f32_e32 v126, v126
	v_cndmask_b32_e64 v102, v121, v186, s[98:99]
	v_fma_f32 v98, v6, v182, v170
	v_cndmask_b32_e64 v103, v125, v187, s[100:101]
	v_fmac_f32_e32 v98, v178, v102
	v_cndmask_b32_e64 v190, v110, v121, s[98:99]
	v_fma_f32 v114, v114, v182, v170
; __device__ __forceinline__ unsigned cvt_pk_bf16(float lo, float hi) { unsigned r; asm volatile("v_cvt_pk_bf16_f32 %0, %1, %2" : "=v"(r) : "v"(lo), "v"(hi)); return r; }
; __device__ __forceinline__ float siluf(float x) { return x * __builtin_amdgcn_rcpf(1.f + __expf(-x)); }
;     __device__ __forceinline__ void operator()(const f32x4 (&acc)[2][2][4][2], const pg8::Unit& u, int wr, int wc, int fr, int fq) const {
;     ...
;             const int chp = ch0 + 2 * cp;
;             const f32x2 wa0 = *(const f32x2*)(wconv + chp), wa1 = *(const f32x2*)(wconv + NUP + chp), wa2 = *(const f32x2*)(wconv + 2 * NUP + chp), ba = *(const f32x2*)(bconv + chp);
;             const f32x2 wb0 = *(const f32x2*)(wconv + DFF + chp), wb1 = *(const f32x2*)(wconv + NUP + DFF + chp), wb2 = *(const f32x2*)(wconv + 2 * NUP + DFF + chp), bb = *(const f32x2*)(bconv + DFF + chp);
;     ...
;             for (int ai = 0; ai < 2; ++ai) {
;                 float rr[4][2];
; #pragma unroll
;                 for (int ii = 0; ii < 2; ++ii) {
;                     const int c8 = 2 * cp + ii, n = c8 >> 2, i = c8 & 3;
;                     float ua[4], ub[4], r1a[4], r2a[4], r1b[4], r2b[4];
; #pragma unroll
;                     for (int m = 0; m < 4; ++m) { ua[m] = acc[ai][0][m][n][i]; ub[m] = acc[ai][1][m][n][i];
;                         r1a[m] = dpp_ror<0x121>(ua[m]); r2a[m] = dpp_ror<0x122>(ua[m]); r1b[m] = dpp_ror<0x121>(ub[m]); r2b[m] = dpp_ror<0x122>(ub[m]); }
; #pragma unroll
;                     for (int m = 0; m < 4; ++m) {
;                         const float p1a = fr >= 1 ? r1a[m] : r1a[(m + 3) & 3], p2a = fr >= 2 ? r2a[m] : r2a[(m + 3) & 3];
;                         const float p1b = fr >= 1 ? r1b[m] : r1b[(m + 3) & 3], p2b = fr >= 2 ? r2b[m] : r2b[(m + 3) & 3];
;                         const float ca = ba[ii] + wa2[ii] * ua[m] + wa1[ii] * p1a + wa0[ii] * p2a;
;                         const float cb = bb[ii] + wb2[ii] * ub[m] + wb1[ii] * p1b + wb0[ii] * p2b;
;                         rr[m][ii] = siluf(ca) * cb;
;                     }
;                 }
; #pragma unroll
;                 for (int m = 0; m < 4; ++m) outp[ai][m][cp] = pg8::cvt_pk_bf16(rr[m][0], rr[m][1]);
	v_fmac_f32_e32 v98, v176, v103
	v_mul_f32_e32 v99, v106, v99
	v_cndmask_b32_e64 v191, v111, v125, s[100:101]
	v_fmac_f32_e32 v114, v178, v190
	v_mul_f32_e32 v98, v98, v99
	v_fmac_f32_e32 v114, v176, v191
	v_mul_f32_e32 v118, v118, v126
	v_mov_b32_dpp v99, v31 row_ror:1 row_mask:0xf bank_mask:0xf
	v_mov_b32_dpp v107, v127 row_ror:1 row_mask:0xf bank_mask:0xf
	v_mul_f32_e32 v114, v114, v118
	v_mov_b32_dpp v102, v31 row_ror:2 row_mask:0xf bank_mask:0xf
	v_mov_b32_dpp v110, v127 row_ror:2 row_mask:0xf bank_mask:0xf
	v_mov_b32_dpp v117, v119 row_ror:1 row_mask:0xf bank_mask:0xf
	v_mov_b32_dpp v118, v119 row_ror:2 row_mask:0xf bank_mask:0xf
	v_mov_b32_dpp v126, v15 row_ror:1 row_mask:0xf bank_mask:0xf
	v_mov_b32_dpp v168, v15 row_ror:2 row_mask:0xf bank_mask:0xf
	v_cndmask_b32_e64 v174, v126, v99, s[98:99]
	v_fma_f32 v182, v31, v181, v169
	v_cndmask_b32_e64 v176, v168, v102, s[100:101]
	v_fmac_f32_e32 v182, v175, v174
	v_fmac_f32_e32 v182, v173, v176
	v_mul_f32_e32 v176, 0xbfb8aa3b, v182
	v_exp_f32_e32 v176, v176
	v_mov_b32_dpp v103, v23 row_ror:1 row_mask:0xf bank_mask:0xf
	v_mov_b32_dpp v111, v123 row_ror:1 row_mask:0xf bank_mask:0xf
	v_add_f32_e32 v176, 1.0, v176
	v_mov_b32_dpp v106, v23 row_ror:2 row_mask:0xf bank_mask:0xf
	v_mov_b32_dpp v113, v123 row_ror:2 row_mask:0xf bank_mask:0xf
	v_mov_b32_dpp v121, v115 row_ror:1 row_mask:0xf bank_mask:0xf
	v_rcp_f32_e32 v176, v176
	v_mov_b32_dpp v125, v115 row_ror:2 row_mask:0xf bank_mask:0xf
	v_mov_b32_dpp v170, v7 row_ror:1 row_mask:0xf bank_mask:0xf
	v_mov_b32_dpp v172, v7 row_ror:2 row_mask:0xf bank_mask:0xf
	v_cndmask_b32_e64 v178, v170, v103, s[98:99]
	v_fma_f32 v174, v23, v183, v171
	v_cndmask_b32_e64 v180, v172, v106, s[100:101]
	v_fmac_f32_e32 v174, v179, v178
	v_fmac_f32_e32 v174, v177, v180
	v_mul_f32_e32 v176, v182, v176
	v_mul_f32_e32 v174, v174, v176
	v_cndmask_b32_e64 v176, v99, v107, s[98:99]
	v_fma_f32 v127, v127, v181, v169
	v_cndmask_b32_e64 v178, v102, v110, s[100:101]
	v_fmac_f32_e32 v127, v175, v176
	v_fmac_f32_e32 v127, v173, v178
	v_mul_f32_e32 v176, 0xbfb8aa3b, v127
	v_exp_f32_e32 v176, v176
	s_nop 0
	v_add_f32_e32 v176, 1.0, v176
	v_rcp_f32_e32 v176, v176
	v_cndmask_b32_e64 v180, v103, v111, s[98:99]
	v_fma_f32 v123, v123, v183, v171
	v_cndmask_b32_e64 v182, v106, v113, s[100:101]
	v_fmac_f32_e32 v123, v179, v180
	v_fmac_f32_e32 v123, v177, v182
	v_mul_f32_e32 v127, v127, v176
	v_mul_f32_e32 v123, v123, v127
	v_cndmask_b32_e64 v127, v107, v117, s[98:99]
	v_fma_f32 v119, v119, v181, v169
	v_cndmask_b32_e64 v99, v117, v126, s[98:99]
	v_fmac_f32_e32 v169, v15, v181
	v_cndmask_b32_e64 v176, v110, v118, s[100:101]
	v_fmac_f32_e32 v119, v175, v127
	v_cndmask_b32_e64 v102, v118, v168, s[100:101]
	v_fmac_f32_e32 v169, v175, v99
	v_fmac_f32_e32 v119, v173, v176
	v_fmac_f32_e32 v169, v173, v102
	v_mul_f32_e32 v127, 0xbfb8aa3b, v119
	v_mul_f32_e32 v99, 0xbfb8aa3b, v169
	v_exp_f32_e32 v127, v127
	v_exp_f32_e32 v99, v99
	v_add_f32_e32 v127, 1.0, v127
	v_add_f32_e32 v99, 1.0, v99
	v_rcp_f32_e32 v127, v127
	v_rcp_f32_e32 v99, v99
	v_cndmask_b32_e64 v178, v111, v121, s[98:99]
	v_fma_f32 v115, v115, v183, v171
	v_cndmask_b32_e64 v103, v121, v170, s[98:99]
	v_fmac_f32_e32 v171, v7, v183
	v_cndmask_b32_e64 v180, v113, v125, s[100:101]
	v_fmac_f32_e32 v115, v179, v178
	v_cndmask_b32_e64 v106, v125, v172, s[100:101]
	v_fmac_f32_e32 v171, v179, v103
	v_fmac_f32_e32 v115, v177, v180
	v_mul_f32_e32 v119, v119, v127
	v_fmac_f32_e32 v171, v177, v106
	v_mul_f32_e32 v99, v169, v99
	v_mul_f32_e32 v115, v115, v119
	v_mul_f32_e32 v99, v171, v99
	v_cvt_pk_bf16_f32 v125, v188, v174
	v_cvt_pk_bf16_f32 v121, v122, v123
	v_cvt_pk_bf16_f32 v117, v114, v115
	v_cvt_pk_bf16_f32 v113, v98, v99
	v_or_b32_e32 v98, 4, v162
	v_ashrrev_i32_e32 v99, 31, v98
	v_lshlrev_b64 v[98:99], 2, v[98:99]
	v_lshl_add_u64 v[102:103], s[80:81], 0, v[98:99]
	global_load_dwordx2 v[126:127], v[102:103], off
	v_lshl_add_u64 v[102:103], s[82:83], 0, v[98:99]
	global_load_dwordx2 v[122:123], v[164:165], off offset:16
	global_load_dwordx2 v[172:173], v[102:103], off
	global_load_dwordx2 v[114:115], v[166:167], off offset:16
	v_lshl_add_u64 v[102:103], s[84:85], 0, v[98:99]
	global_load_dwordx2 v[168:169], v[102:103], off
	v_lshl_add_u64 v[102:103], s[90:91], 0, v[98:99]
	global_load_dwordx2 v[170:171], v[102:103], off
	v_lshl_add_u64 v[102:103], s[92:93], 0, v[98:99]
	v_lshl_add_u64 v[98:99], s[94:95], 0, v[98:99]
	global_load_dwordx2 v[174:175], v[102:103], off
	global_load_dwordx2 v[118:119], v[98:99], off
	v_mov_b32_dpp v182, v56 row_ror:1 row_mask:0xf bank_mask:0xf
	v_mov_b32_dpp v186, v92 row_ror:1 row_mask:0xf bank_mask:0xf
	v_mov_b32_dpp v190, v84 row_ror:1 row_mask:0xf bank_mask:0xf
	v_mov_b32_dpp v183, v56 row_ror:2 row_mask:0xf bank_mask:0xf
	v_mov_b32_dpp v187, v92 row_ror:2 row_mask:0xf bank_mask:0xf
	v_mov_b32_dpp v194, v40 row_ror:1 row_mask:0xf bank_mask:0xf
	v_mov_b32_dpp v191, v84 row_ror:2 row_mask:0xf bank_mask:0xf
	v_cndmask_b32_e64 v99, v194, v182, s[98:99]
	v_mov_b32_dpp v184, v48 row_ror:1 row_mask:0xf bank_mask:0xf
	v_mov_b32_dpp v188, v88 row_ror:1 row_mask:0xf bank_mask:0xf
	v_mov_b32_dpp v195, v40 row_ror:2 row_mask:0xf bank_mask:0xf
	v_mov_b32_dpp v185, v48 row_ror:2 row_mask:0xf bank_mask:0xf
	v_mov_b32_dpp v189, v88 row_ror:2 row_mask:0xf bank_mask:0xf
	v_mov_b32_dpp v192, v80 row_ror:1 row_mask:0xf bank_mask:0xf
	v_cndmask_b32_e64 v103, v195, v183, s[100:101]
	v_mov_b32_dpp v193, v80 row_ror:2 row_mask:0xf bank_mask:0xf
	v_mov_b32_dpp v196, v32 row_ror:1 row_mask:0xf bank_mask:0xf
	v_mov_b32_e32 v106, v48
	v_mov_b32_e32 v107, v56
	v_mov_b32_dpp v197, v32 row_ror:2 row_mask:0xf bank_mask:0xf
	v_cndmask_b32_e64 v98, v196, v184, s[98:99]
	v_cndmask_b32_e64 v102, v197, v185, s[100:101]
	v_mov_b32_e32 v180, v88
	v_mov_b32_e32 v181, v92
	v_mov_b32_e32 v92, v89
	s_waitcnt vmcnt(7)
; __device__ __forceinline__ unsigned cvt_pk_bf16(float lo, float hi) { unsigned r; asm volatile("v_cvt_pk_bf16_f32 %0, %1, %2" : "=v"(r) : "v"(lo), "v"(hi)); return r; }
; __device__ __forceinline__ float siluf(float x) { return x * __builtin_amdgcn_rcpf(1.f + __expf(-x)); }
;     __device__ __forceinline__ void operator()(const f32x4 (&acc)[2][2][4][2], const pg8::Unit& u, int wr, int wc, int fr, int fq) const {
;     ...
;             for (int ai = 0; ai < 2; ++ai) {
;                 float rr[4][2];
; #pragma unroll
;                 for (int ii = 0; ii < 2; ++ii) {
;                     const int c8 = 2 * cp + ii, n = c8 >> 2, i = c8 & 3;
;                     float ua[4], ub[4], r1a[4], r2a[4], r1b[4], r2b[4];
; #pragma unroll
;                     for (int m = 0; m < 4; ++m) { ua[m] = acc[ai][0][m][n][i]; ub[m] = acc[ai][1][m][n][i];
;                         r1a[m] = dpp_ror<0x121>(ua[m]); r2a[m] = dpp_ror<0x122>(ua[m]); r1b[m] = dpp_ror<0x121>(ub[m]); r2b[m] = dpp_ror<0x122>(ub[m]); }
; #pragma unroll
;                     for (int m = 0; m < 4; ++m) {
;                         const float p1a = fr >= 1 ? r1a[m] : r1a[(m + 3) & 3], p2a = fr >= 2 ? r2a[m] : r2a[(m + 3) & 3];
;                         const float p1b = fr >= 1 ? r1b[m] : r1b[(m + 3) & 3], p2b = fr >= 2 ? r2b[m] : r2b[(m + 3) & 3];
;                         const float ca = ba[ii] + wa2[ii] * ua[m] + wa1[ii] * p1a + wa0[ii] * p2a;
;                         const float cb = bb[ii] + wb2[ii] * ub[m] + wb1[ii] * p1b + wb0[ii] * p2b;
;                         rr[m][ii] = siluf(ca) * cb;
;                     }
;                 }
; #pragma unroll
;                 for (int m = 0; m < 4; ++m) outp[ai][m][cp] = pg8::cvt_pk_bf16(rr[m][0], rr[m][1]);
	v_mov_b32_e32 v179, v126
	s_waitcnt vmcnt(5)
	v_mov_b32_e32 v111, v172
	s_waitcnt vmcnt(4)
	v_mov_b32_e32 v177, v114
	s_waitcnt vmcnt(2)
	v_mov_b32_e32 v178, v170
	s_waitcnt vmcnt(1)
	v_mov_b32_e32 v110, v174
	s_waitcnt vmcnt(0)
	v_mov_b32_e32 v176, v118
	v_pk_fma_f32 v[106:107], v[106:107], v[110:111], v[176:177]
	v_pk_fma_f32 v[180:181], v[180:181], v[110:111], v[176:177]
	v_pk_fma_f32 v[98:99], v[178:179], v[98:99], v[106:107]
	v_mov_b32_e32 v106, v168
	v_mov_b32_e32 v107, v122
	v_pk_fma_f32 v[98:99], v[106:107], v[102:103], v[98:99]
	s_nop 0
	v_mul_f32_e32 v102, 0xbfb8aa3b, v99
	v_exp_f32_e32 v102, v102
	s_nop 0
	v_add_f32_e32 v102, 1.0, v102
	v_rcp_f32_e32 v102, v102
	s_nop 0
	v_mul_f32_e32 v99, v99, v102
	v_mul_f32_e32 v198, v98, v99
	v_cndmask_b32_e64 v99, v182, v186, s[98:99]
	v_cndmask_b32_e64 v103, v183, v187, s[100:101]
	v_cndmask_b32_e64 v98, v184, v188, s[98:99]
	v_cndmask_b32_e64 v102, v185, v189, s[100:101]
	v_pk_fma_f32 v[98:99], v[178:179], v[98:99], v[180:181]
	v_mov_b32_e32 v180, v80
	v_pk_fma_f32 v[98:99], v[106:107], v[102:103], v[98:99]
	v_mov_b32_e32 v181, v84
	v_mul_f32_e32 v88, 0xbfb8aa3b, v99
	v_exp_f32_e32 v88, v88
	v_pk_fma_f32 v[180:181], v[180:181], v[110:111], v[176:177]
	v_mov_b32_e32 v84, v81
	v_add_f32_e32 v88, 1.0, v88
	v_rcp_f32_e32 v88, v88
	s_nop 0
	v_mul_f32_e32 v88, v99, v88
	v_mul_f32_e32 v199, v98, v88
	v_cndmask_b32_e64 v99, v186, v190, s[98:99]
	v_cndmask_b32_e64 v103, v187, v191, s[100:101]
	v_cndmask_b32_e64 v98, v188, v192, s[98:99]
	v_cndmask_b32_e64 v102, v189, v193, s[100:101]
	v_pk_fma_f32 v[98:99], v[178:179], v[98:99], v[180:181]
	v_mov_b32_e32 v180, v32
	v_pk_fma_f32 v[98:99], v[106:107], v[102:103], v[98:99]
	v_mov_b32_e32 v181, v40
	v_mul_f32_e32 v80, 0xbfb8aa3b, v99
	v_exp_f32_e32 v80, v80
	v_pk_fma_f32 v[110:111], v[180:181], v[110:111], v[176:177]
	v_mov_b32_e32 v176, v119
	v_add_f32_e32 v80, 1.0, v80
	v_rcp_f32_e32 v80, v80
	v_mov_b32_dpp v181, v57 row_ror:1 row_mask:0xf bank_mask:0xf
	v_mov_b32_e32 v177, v115
	v_mul_f32_e32 v80, v99, v80
	v_mul_f32_e32 v200, v98, v80
	v_cndmask_b32_e64 v99, v190, v194, s[98:99]
	v_cndmask_b32_e64 v103, v191, v195, s[100:101]
	v_cndmask_b32_e64 v98, v192, v196, s[98:99]
	v_cndmask_b32_e64 v102, v193, v197, s[100:101]
	v_pk_fma_f32 v[98:99], v[178:179], v[98:99], v[110:111]
	v_pk_fma_f32 v[98:99], v[106:107], v[102:103], v[98:99]
	v_mul_f32_e32 v80, 0xbfb8aa3b, v99
	v_exp_f32_e32 v80, v80
	v_mov_b32_dpp v185, v93 row_ror:1 row_mask:0xf bank_mask:0xf
	v_add_f32_e32 v80, 1.0, v80
	v_rcp_f32_e32 v80, v80
	v_mov_b32_dpp v189, v85 row_ror:1 row_mask:0xf bank_mask:0xf
	v_mov_b32_dpp v182, v57 row_ror:2 row_mask:0xf bank_mask:0xf
	v_mul_f32_e32 v80, v99, v80
	v_mul_f32_e32 v180, v98, v80
	v_mov_b32_dpp v186, v93 row_ror:2 row_mask:0xf bank_mask:0xf
	v_mov_b32_dpp v193, v41 row_ror:1 row_mask:0xf bank_mask:0xf
	v_mov_b32_dpp v190, v85 row_ror:2 row_mask:0xf bank_mask:0xf
	v_cndmask_b32_e64 v99, v193, v181, s[98:99]
	v_mov_b32_dpp v183, v49 row_ror:1 row_mask:0xf bank_mask:0xf
	v_mov_b32_dpp v187, v89 row_ror:1 row_mask:0xf bank_mask:0xf
	v_mov_b32_dpp v194, v41 row_ror:2 row_mask:0xf bank_mask:0xf
	v_mov_b32_dpp v191, v81 row_ror:1 row_mask:0xf bank_mask:0xf
	v_cndmask_b32_e64 v103, v194, v182, s[100:101]
	v_mov_b32_dpp v184, v49 row_ror:2 row_mask:0xf bank_mask:0xf
	v_mov_b32_dpp v188, v89 row_ror:2 row_mask:0xf bank_mask:0xf
	v_mov_b32_dpp v195, v33 row_ror:1 row_mask:0xf bank_mask:0xf
	v_mov_b32_dpp v192, v81 row_ror:2 row_mask:0xf bank_mask:0xf
	v_cndmask_b32_e64 v98, v195, v183, s[98:99]
	v_mov_b32_e32 v106, v49
	v_mov_b32_e32 v107, v57
	v_mov_b32_e32 v110, v175
	v_mov_b32_e32 v111, v173
	v_mov_b32_dpp v196, v33 row_ror:2 row_mask:0xf bank_mask:0xf
	v_pk_fma_f32 v[106:107], v[106:107], v[110:111], v[176:177]
	v_mov_b32_e32 v178, v171
	v_mov_b32_e32 v179, v127
	v_cndmask_b32_e64 v102, v196, v184, s[100:101]
	v_pk_fma_f32 v[98:99], v[178:179], v[98:99], v[106:107]
	v_mov_b32_e32 v106, v169
	v_mov_b32_e32 v107, v123
	v_pk_fma_f32 v[98:99], v[106:107], v[102:103], v[98:99]
	v_pk_fma_f32 v[88:89], v[92:93], v[110:111], v[176:177]
	v_mul_f32_e32 v80, 0xbfb8aa3b, v99
	v_exp_f32_e32 v80, v80
	s_nop 0
	v_add_f32_e32 v80, 1.0, v80
	v_rcp_f32_e32 v80, v80
	s_nop 0
	v_mul_f32_e32 v80, v99, v80
	v_mul_f32_e32 v197, v98, v80
	v_cndmask_b32_e64 v99, v181, v185, s[98:99]
	v_cndmask_b32_e64 v103, v182, v186, s[100:101]
	v_cndmask_b32_e64 v98, v183, v187, s[98:99]
	v_cndmask_b32_e64 v102, v184, v188, s[100:101]
	v_pk_fma_f32 v[88:89], v[178:179], v[98:99], v[88:89]
	v_pk_fma_f32 v[88:89], v[106:107], v[102:103], v[88:89]
	v_mul_f32_e32 v80, 0xbfb8aa3b, v89
	v_exp_f32_e32 v80, v80
	v_mov_b32_dpp v99, v68 row_ror:1 row_mask:0xf bank_mask:0xf
	v_mov_b32_dpp v103, v68 row_ror:2 row_mask:0xf bank_mask:0xf
	v_fma_f32 v68, v68, v172, v114
	v_add_f32_e32 v80, 1.0, v80
	v_rcp_f32_e32 v80, v80
	s_nop 0
	v_mul_f32_e32 v80, v89, v80
	v_mul_f32_e32 v98, v88, v80
	v_cndmask_b32_e64 v89, v185, v189, s[98:99]
	v_cndmask_b32_e64 v93, v186, v190, s[100:101]
	v_cndmask_b32_e64 v88, v187, v191, s[98:99]
	v_cndmask_b32_e64 v92, v188, v192, s[100:101]
	v_pk_fma_f32 v[80:81], v[84:85], v[110:111], v[176:177]
	s_nop 0
	v_pk_fma_f32 v[80:81], v[178:179], v[88:89], v[80:81]
	v_mov_b32_e32 v88, v33
	v_pk_fma_f32 v[80:81], v[106:107], v[92:93], v[80:81]
	v_mov_b32_e32 v89, v41
	v_mul_f32_e32 v84, 0xbfb8aa3b, v81
	v_exp_f32_e32 v84, v84
	v_pk_fma_f32 v[88:89], v[88:89], v[110:111], v[176:177]
	v_cvt_pk_bf16_f32 v110, v198, v197
	v_add_f32_e32 v84, 1.0, v84
	v_rcp_f32_e32 v84, v84
	v_mov_b32_dpp v176, v8 row_ror:1 row_mask:0xf bank_mask:0xf
	v_mov_b32_e32 v93, 0
	v_mul_f32_e32 v81, v81, v84
; __device__ __forceinline__ unsigned cvt_pk_bf16(float lo, float hi) { unsigned r; asm volatile("v_cvt_pk_bf16_f32 %0, %1, %2" : "=v"(r) : "v"(lo), "v"(hi)); return r; }
; __device__ __forceinline__ float siluf(float x) { return x * __builtin_amdgcn_rcpf(1.f + __expf(-x)); }
;     __device__ __forceinline__ void operator()(const f32x4 (&acc)[2][2][4][2], const pg8::Unit& u, int wr, int wc, int fr, int fq) const {
;     ...
;             for (int ai = 0; ai < 2; ++ai) {
;                 float rr[4][2];
; #pragma unroll
;                 for (int ii = 0; ii < 2; ++ii) {
;                     const int c8 = 2 * cp + ii, n = c8 >> 2, i = c8 & 3;
;                     float ua[4], ub[4], r1a[4], r2a[4], r1b[4], r2b[4];
; #pragma unroll
;                     for (int m = 0; m < 4; ++m) { ua[m] = acc[ai][0][m][n][i]; ub[m] = acc[ai][1][m][n][i];
;                         r1a[m] = dpp_ror<0x121>(ua[m]); r2a[m] = dpp_ror<0x122>(ua[m]); r1b[m] = dpp_ror<0x121>(ub[m]); r2b[m] = dpp_ror<0x122>(ub[m]); }
; #pragma unroll
;                     for (int m = 0; m < 4; ++m) {
;                         const float p1a = fr >= 1 ? r1a[m] : r1a[(m + 3) & 3], p2a = fr >= 2 ? r2a[m] : r2a[(m + 3) & 3];
;                         const float p1b = fr >= 1 ? r1b[m] : r1b[(m + 3) & 3], p2b = fr >= 2 ? r2b[m] : r2b[(m + 3) & 3];
;                         const float ca = ba[ii] + wa2[ii] * ua[m] + wa1[ii] * p1a + wa0[ii] * p2a;
;                         const float cb = bb[ii] + wb2[ii] * ub[m] + wb1[ii] * p1b + wb0[ii] * p2b;
;                         rr[m][ii] = siluf(ca) * cb;
;                     }
;                 }
; #pragma unroll
;                 for (int m = 0; m < 4; ++m) outp[ai][m][cp] = pg8::cvt_pk_bf16(rr[m][0], rr[m][1]);
	v_mul_f32_e32 v92, v80, v81
	v_cndmask_b32_e64 v81, v189, v193, s[98:99]
	v_cndmask_b32_e64 v85, v190, v194, s[100:101]
	v_cndmask_b32_e64 v80, v191, v195, s[98:99]
	v_cndmask_b32_e64 v84, v192, v196, s[100:101]
	v_pk_fma_f32 v[80:81], v[178:179], v[80:81], v[88:89]
	v_pk_fma_f32 v[80:81], v[106:107], v[84:85], v[80:81]
	v_cvt_pk_bf16_f32 v106, v199, v98
	v_cvt_pk_bf16_f32 v102, v200, v92
	v_mul_f32_e32 v84, 0xbfb8aa3b, v81
	v_exp_f32_e32 v84, v84
	v_mov_b32_dpp v88, v76 row_ror:1 row_mask:0xf bank_mask:0xf
	v_mov_b32_dpp v89, v76 row_ror:2 row_mask:0xf bank_mask:0xf
	v_mov_b32_dpp v177, v8 row_ror:2 row_mask:0xf bank_mask:0xf
	v_add_f32_e32 v84, 1.0, v84
	v_rcp_f32_e32 v84, v84
	v_fma_f32 v184, v24, v172, v114
	v_mul_f32_e32 v81, v81, v84
	v_mul_f32_e32 v80, v80, v81
	v_cvt_pk_bf16_f32 v98, v180, v80
	s_nop 0
	v_mov_b32_dpp v80, v24 row_ror:1 row_mask:0xf bank_mask:0xf
	v_mov_b32_dpp v81, v24 row_ror:2 row_mask:0xf bank_mask:0xf
	v_cndmask_b32_e64 v180, v176, v80, s[98:99]
	v_cndmask_b32_e64 v181, v177, v81, s[100:101]
	v_fmac_f32_e32 v184, v126, v180
	v_fmac_f32_e32 v184, v122, v181
	v_mul_f32_e32 v181, 0xbfb8aa3b, v184
	v_exp_f32_e32 v181, v181
	v_mov_b32_dpp v84, v16 row_ror:1 row_mask:0xf bank_mask:0xf
	v_mov_b32_dpp v92, v72 row_ror:1 row_mask:0xf bank_mask:0xf
	v_add_f32_e32 v181, 1.0, v181
	v_mov_b32_dpp v85, v16 row_ror:2 row_mask:0xf bank_mask:0xf
	v_mov_b32_dpp v93, v72 row_ror:2 row_mask:0xf bank_mask:0xf
	v_mov_b32_dpp v107, v64 row_ror:1 row_mask:0xf bank_mask:0xf
	v_rcp_f32_e32 v181, v181
	v_mov_b32_dpp v111, v64 row_ror:2 row_mask:0xf bank_mask:0xf
	v_mov_b32_dpp v178, v0 row_ror:1 row_mask:0xf bank_mask:0xf
	v_mov_b32_dpp v179, v0 row_ror:2 row_mask:0xf bank_mask:0xf
	v_cndmask_b32_e64 v182, v178, v84, s[98:99]
	v_fma_f32 v180, v16, v174, v118
	v_cndmask_b32_e64 v183, v179, v85, s[100:101]
	v_fmac_f32_e32 v180, v170, v182
	v_fmac_f32_e32 v180, v168, v183
	v_mul_f32_e32 v181, v184, v181
	v_mul_f32_e32 v180, v180, v181
	v_cndmask_b32_e64 v181, v80, v88, s[98:99]
	v_fma_f32 v76, v76, v172, v114
	v_cndmask_b32_e64 v182, v81, v89, s[100:101]
	v_fmac_f32_e32 v76, v126, v181
	v_fmac_f32_e32 v76, v122, v182
	v_mul_f32_e32 v181, 0xbfb8aa3b, v76
	v_exp_f32_e32 v181, v181
	s_nop 0
	v_add_f32_e32 v181, 1.0, v181
	v_rcp_f32_e32 v181, v181
	v_cndmask_b32_e64 v183, v84, v92, s[98:99]
	v_fma_f32 v72, v72, v174, v118
	v_cndmask_b32_e64 v184, v85, v93, s[100:101]
	v_fmac_f32_e32 v72, v170, v183
	v_fmac_f32_e32 v72, v168, v184
	v_mul_f32_e32 v76, v76, v181
	v_mul_f32_e32 v72, v72, v76
	v_cndmask_b32_e64 v76, v88, v99, s[98:99]
	v_cndmask_b32_e64 v181, v89, v103, s[100:101]
	v_fmac_f32_e32 v68, v126, v76
	v_fmac_f32_e32 v68, v122, v181
	v_mul_f32_e32 v76, 0xbfb8aa3b, v68
	v_exp_f32_e32 v76, v76
	s_nop 0
	v_add_f32_e32 v76, 1.0, v76
	v_rcp_f32_e32 v76, v76
	v_cndmask_b32_e64 v182, v92, v107, s[98:99]
	v_fma_f32 v64, v64, v174, v118
	v_cndmask_b32_e64 v183, v93, v111, s[100:101]
	v_fmac_f32_e32 v64, v170, v182
	v_fmac_f32_e32 v64, v168, v183
	v_mul_f32_e32 v68, v68, v76
	v_mul_f32_e32 v64, v64, v68
	v_cndmask_b32_e64 v68, v99, v176, s[98:99]
	v_fma_f32 v84, v8, v172, v114
	v_cndmask_b32_e64 v76, v103, v177, s[100:101]
	v_fmac_f32_e32 v84, v126, v68
	v_fmac_f32_e32 v84, v122, v76
	v_mul_f32_e32 v76, 0xbfb8aa3b, v84
	v_exp_f32_e32 v76, v76
	v_cndmask_b32_e64 v80, v107, v178, s[98:99]
	v_add_f32_e32 v76, 1.0, v76
	v_rcp_f32_e32 v76, v76
	v_fma_f32 v68, v0, v174, v118
	v_cndmask_b32_e64 v81, v111, v179, s[100:101]
	v_fmac_f32_e32 v68, v170, v80
	v_fmac_f32_e32 v68, v168, v81
	v_mul_f32_e32 v76, v84, v76
	v_mul_f32_e32 v68, v68, v76
	s_nop 0
	v_mov_b32_dpp v76, v25 row_ror:1 row_mask:0xf bank_mask:0xf
	v_mov_b32_dpp v85, v77 row_ror:1 row_mask:0xf bank_mask:0xf
	v_mov_b32_dpp v80, v25 row_ror:2 row_mask:0xf bank_mask:0xf
	v_mov_b32_dpp v88, v77 row_ror:2 row_mask:0xf bank_mask:0xf
	v_mov_b32_dpp v93, v69 row_ror:1 row_mask:0xf bank_mask:0xf
	v_mov_b32_dpp v99, v69 row_ror:2 row_mask:0xf bank_mask:0xf
	v_mov_b32_dpp v111, v9 row_ror:1 row_mask:0xf bank_mask:0xf
	v_mov_b32_dpp v114, v9 row_ror:2 row_mask:0xf bank_mask:0xf
	v_cndmask_b32_e64 v126, v111, v76, s[98:99]
	v_fma_f32 v174, v25, v173, v115
	v_cndmask_b32_e64 v168, v114, v80, s[100:101]
	v_fmac_f32_e32 v174, v127, v126
	v_fmac_f32_e32 v174, v123, v168
	v_mul_f32_e32 v168, 0xbfb8aa3b, v174
	v_exp_f32_e32 v168, v168
	v_mov_b32_dpp v81, v17 row_ror:1 row_mask:0xf bank_mask:0xf
	v_mov_b32_dpp v89, v73 row_ror:1 row_mask:0xf bank_mask:0xf
	v_add_f32_e32 v168, 1.0, v168
	v_mov_b32_dpp v84, v17 row_ror:2 row_mask:0xf bank_mask:0xf
	v_mov_b32_dpp v92, v73 row_ror:2 row_mask:0xf bank_mask:0xf
	v_mov_b32_dpp v103, v65 row_ror:1 row_mask:0xf bank_mask:0xf
	v_rcp_f32_e32 v168, v168
	v_mov_b32_dpp v107, v65 row_ror:2 row_mask:0xf bank_mask:0xf
	v_mov_b32_dpp v118, v1 row_ror:1 row_mask:0xf bank_mask:0xf
	v_mov_b32_dpp v122, v1 row_ror:2 row_mask:0xf bank_mask:0xf
	v_cndmask_b32_e64 v170, v118, v81, s[98:99]
	v_fma_f32 v126, v17, v175, v119
	v_cndmask_b32_e64 v172, v122, v84, s[100:101]
	v_fmac_f32_e32 v126, v171, v170
	v_fmac_f32_e32 v126, v169, v172
	v_mul_f32_e32 v168, v174, v168
	v_mul_f32_e32 v126, v126, v168
	v_cndmask_b32_e64 v168, v76, v85, s[98:99]
	v_fma_f32 v77, v77, v173, v115
	v_cndmask_b32_e64 v170, v80, v88, s[100:101]
	v_fmac_f32_e32 v77, v127, v168
	v_fmac_f32_e32 v77, v123, v170
	v_mul_f32_e32 v168, 0xbfb8aa3b, v77
	v_exp_f32_e32 v168, v168
	s_nop 0
	v_add_f32_e32 v168, 1.0, v168
	v_rcp_f32_e32 v168, v168
	v_cndmask_b32_e64 v172, v81, v89, s[98:99]
	v_fma_f32 v73, v73, v175, v119
	v_cndmask_b32_e64 v174, v84, v92, s[100:101]
	v_fmac_f32_e32 v73, v171, v172
	v_fmac_f32_e32 v73, v169, v174
; __device__ __forceinline__ unsigned cvt_pk_bf16(float lo, float hi) { unsigned r; asm volatile("v_cvt_pk_bf16_f32 %0, %1, %2" : "=v"(r) : "v"(lo), "v"(hi)); return r; }
; __device__ __forceinline__ float siluf(float x) { return x * __builtin_amdgcn_rcpf(1.f + __expf(-x)); }
;     __device__ __forceinline__ void operator()(const f32x4 (&acc)[2][2][4][2], const pg8::Unit& u, int wr, int wc, int fr, int fq) const {
;     ...
;             const int chp = ch0 + 2 * cp;
;             const f32x2 wa0 = *(const f32x2*)(wconv + chp), wa1 = *(const f32x2*)(wconv + NUP + chp), wa2 = *(const f32x2*)(wconv + 2 * NUP + chp), ba = *(const f32x2*)(bconv + chp);
;             const f32x2 wb0 = *(const f32x2*)(wconv + DFF + chp), wb1 = *(const f32x2*)(wconv + NUP + DFF + chp), wb2 = *(const f32x2*)(wconv + 2 * NUP + DFF + chp), bb = *(const f32x2*)(bconv + DFF + chp);
;     ...
;             for (int ai = 0; ai < 2; ++ai) {
;                 float rr[4][2];
; #pragma unroll
;                 for (int ii = 0; ii < 2; ++ii) {
;                     const int c8 = 2 * cp + ii, n = c8 >> 2, i = c8 & 3;
;                     float ua[4], ub[4], r1a[4], r2a[4], r1b[4], r2b[4];
; #pragma unroll
;                     for (int m = 0; m < 4; ++m) { ua[m] = acc[ai][0][m][n][i]; ub[m] = acc[ai][1][m][n][i];
;                         r1a[m] = dpp_ror<0x121>(ua[m]); r2a[m] = dpp_ror<0x122>(ua[m]); r1b[m] = dpp_ror<0x121>(ub[m]); r2b[m] = dpp_ror<0x122>(ub[m]); }
; #pragma unroll
;                     for (int m = 0; m < 4; ++m) {
;                         const float p1a = fr >= 1 ? r1a[m] : r1a[(m + 3) & 3], p2a = fr >= 2 ? r2a[m] : r2a[(m + 3) & 3];
;                         const float p1b = fr >= 1 ? r1b[m] : r1b[(m + 3) & 3], p2b = fr >= 2 ? r2b[m] : r2b[(m + 3) & 3];
;                         const float ca = ba[ii] + wa2[ii] * ua[m] + wa1[ii] * p1a + wa0[ii] * p2a;
;                         const float cb = bb[ii] + wb2[ii] * ub[m] + wb1[ii] * p1b + wb0[ii] * p2b;
;                         rr[m][ii] = siluf(ca) * cb;
;                     }
;                 }
; #pragma unroll
;                 for (int m = 0; m < 4; ++m) outp[ai][m][cp] = pg8::cvt_pk_bf16(rr[m][0], rr[m][1]);
	v_mul_f32_e32 v77, v77, v168
	v_mul_f32_e32 v73, v73, v77
	v_cndmask_b32_e64 v77, v85, v93, s[98:99]
	v_fma_f32 v69, v69, v173, v115
	v_cndmask_b32_e64 v168, v88, v99, s[100:101]
	v_fmac_f32_e32 v69, v127, v77
	v_fmac_f32_e32 v69, v123, v168
	v_mul_f32_e32 v77, 0xbfb8aa3b, v69
	v_exp_f32_e32 v77, v77
	s_nop 0
	v_add_f32_e32 v77, 1.0, v77
	v_rcp_f32_e32 v77, v77
	v_cndmask_b32_e64 v170, v89, v103, s[98:99]
	v_fma_f32 v65, v65, v175, v119
	v_cndmask_b32_e64 v172, v92, v107, s[100:101]
	v_fmac_f32_e32 v65, v171, v170
	v_fmac_f32_e32 v65, v169, v172
	v_mul_f32_e32 v69, v69, v77
	v_mul_f32_e32 v65, v65, v69
	v_cndmask_b32_e64 v69, v93, v111, s[98:99]
	v_fmac_f32_e32 v115, v9, v173
	v_cndmask_b32_e64 v76, v99, v114, s[100:101]
	v_fmac_f32_e32 v115, v127, v69
	v_fmac_f32_e32 v115, v123, v76
	v_mul_f32_e32 v69, 0xbfb8aa3b, v115
	v_exp_f32_e32 v69, v69
	s_nop 0
	v_add_f32_e32 v69, 1.0, v69
	v_rcp_f32_e32 v69, v69
	v_cndmask_b32_e64 v77, v103, v118, s[98:99]
	v_fmac_f32_e32 v119, v1, v175
	v_cndmask_b32_e64 v80, v107, v122, s[100:101]
	v_fmac_f32_e32 v119, v171, v77
	v_fmac_f32_e32 v119, v169, v80
	v_mul_f32_e32 v69, v115, v69
	v_cvt_pk_bf16_f32 v126, v180, v126
	v_cvt_pk_bf16_f32 v122, v72, v73
	v_cvt_pk_bf16_f32 v118, v64, v65
	v_or_b32_e32 v64, 6, v162
	v_mul_f32_e32 v69, v119, v69
	v_ashrrev_i32_e32 v65, 31, v64
	v_cvt_pk_bf16_f32 v114, v68, v69
	v_lshlrev_b64 v[68:69], 2, v[64:65]
	v_lshl_add_u64 v[64:65], s[80:81], 0, v[68:69]
	global_load_dwordx2 v[76:77], v[64:65], off
	v_lshl_add_u64 v[64:65], s[82:83], 0, v[68:69]
	v_lshl_add_u64 v[80:81], s[84:85], 0, v[68:69]
	v_lshl_add_u64 v[84:85], s[90:91], 0, v[68:69]
	v_lshl_add_u64 v[92:93], s[92:93], 0, v[68:69]
	v_lshl_add_u64 v[68:69], s[94:95], 0, v[68:69]
	global_load_dwordx2 v[72:73], v[164:165], off offset:24
	global_load_dwordx2 v[88:89], v[64:65], off
	s_nop 0
	global_load_dwordx2 v[64:65], v[166:167], off offset:24
	global_load_dwordx2 v[92:93], v[92:93], off
	global_load_dwordx2 v[68:69], v[68:69], off
	v_mov_b32_dpp v99, v58 row_ror:1 row_mask:0xf bank_mask:0xf
	global_load_dwordx2 v[84:85], v[84:85], off
	v_mov_b32_dpp v115, v94 row_ror:1 row_mask:0xf bank_mask:0xf
	global_load_dwordx2 v[80:81], v[80:81], off
	v_mov_b32_dpp v178, v86 row_ror:1 row_mask:0xf bank_mask:0xf
	v_mov_b32_dpp v103, v58 row_ror:2 row_mask:0xf bank_mask:0xf
	v_mov_b32_dpp v119, v94 row_ror:2 row_mask:0xf bank_mask:0xf
	v_mov_b32_dpp v182, v42 row_ror:1 row_mask:0xf bank_mask:0xf
	v_mov_b32_dpp v179, v86 row_ror:2 row_mask:0xf bank_mask:0xf
	v_cndmask_b32_e64 v165, v182, v99, s[98:99]
	v_mov_b32_dpp v107, v50 row_ror:1 row_mask:0xf bank_mask:0xf
	v_mov_b32_dpp v123, v90 row_ror:1 row_mask:0xf bank_mask:0xf
	v_mov_b32_dpp v183, v42 row_ror:2 row_mask:0xf bank_mask:0xf
	v_mov_b32_dpp v111, v50 row_ror:2 row_mask:0xf bank_mask:0xf
	v_mov_b32_dpp v127, v90 row_ror:2 row_mask:0xf bank_mask:0xf
	v_mov_b32_dpp v180, v82 row_ror:1 row_mask:0xf bank_mask:0xf
	v_cndmask_b32_e64 v167, v183, v103, s[100:101]
	v_mov_b32_dpp v181, v82 row_ror:2 row_mask:0xf bank_mask:0xf
	v_mov_b32_dpp v184, v34 row_ror:1 row_mask:0xf bank_mask:0xf
	v_mov_b32_e32 v168, v50
	v_mov_b32_e32 v169, v58
	v_mov_b32_dpp v185, v34 row_ror:2 row_mask:0xf bank_mask:0xf
	v_cndmask_b32_e64 v164, v184, v107, s[98:99]
	v_cndmask_b32_e64 v166, v185, v111, s[100:101]
	v_mov_b32_e32 v176, v90
	v_mov_b32_e32 v177, v94
	v_mov_b32_e32 v94, v91
	s_waitcnt vmcnt(7)
	v_mov_b32_e32 v175, v76
	s_waitcnt vmcnt(5)
	v_mov_b32_e32 v171, v88
	s_waitcnt vmcnt(4)
	v_mov_b32_e32 v173, v64
	s_waitcnt vmcnt(3)
	v_mov_b32_e32 v170, v92
	s_waitcnt vmcnt(2)
	v_mov_b32_e32 v172, v68
	v_pk_fma_f32 v[168:169], v[168:169], v[170:171], v[172:173]
	s_waitcnt vmcnt(1)
	v_mov_b32_e32 v174, v84
	v_pk_fma_f32 v[164:165], v[174:175], v[164:165], v[168:169]
	s_waitcnt vmcnt(0)
	v_mov_b32_e32 v168, v80
	v_mov_b32_e32 v169, v72
	v_pk_fma_f32 v[164:165], v[168:169], v[166:167], v[164:165]
	v_pk_fma_f32 v[176:177], v[176:177], v[170:171], v[172:173]
	v_mul_f32_e32 v166, 0xbfb8aa3b, v165
	v_exp_f32_e32 v166, v166
	s_nop 0
	v_add_f32_e32 v166, 1.0, v166
	v_rcp_f32_e32 v166, v166
	s_nop 0
	v_mul_f32_e32 v165, v165, v166
	v_mul_f32_e32 v186, v164, v165
	v_cndmask_b32_e64 v165, v99, v115, s[98:99]
	v_cndmask_b32_e64 v167, v103, v119, s[100:101]
	v_cndmask_b32_e64 v164, v107, v123, s[98:99]
	v_cndmask_b32_e64 v166, v111, v127, s[100:101]
	v_pk_fma_f32 v[164:165], v[174:175], v[164:165], v[176:177]
	v_mov_b32_e32 v176, v82
	v_pk_fma_f32 v[164:165], v[168:169], v[166:167], v[164:165]
	v_mov_b32_e32 v177, v86
	v_mul_f32_e32 v90, 0xbfb8aa3b, v165
	v_exp_f32_e32 v90, v90
	v_pk_fma_f32 v[176:177], v[176:177], v[170:171], v[172:173]
	v_mov_b32_e32 v86, v83
	v_add_f32_e32 v90, 1.0, v90
	v_rcp_f32_e32 v90, v90
	s_nop 0
	v_mul_f32_e32 v90, v165, v90
	v_mul_f32_e32 v187, v164, v90
	v_cndmask_b32_e64 v165, v115, v178, s[98:99]
	v_cndmask_b32_e64 v167, v119, v179, s[100:101]
	v_cndmask_b32_e64 v164, v123, v180, s[98:99]
	v_cndmask_b32_e64 v166, v127, v181, s[100:101]
	v_pk_fma_f32 v[164:165], v[174:175], v[164:165], v[176:177]
	v_mov_b32_e32 v176, v34
	v_pk_fma_f32 v[164:165], v[168:169], v[166:167], v[164:165]
	v_mov_b32_e32 v177, v42
	v_mul_f32_e32 v82, 0xbfb8aa3b, v165
	v_exp_f32_e32 v82, v82
	v_pk_fma_f32 v[170:171], v[176:177], v[170:171], v[172:173]
	v_add_f32_e32 v82, 1.0, v82
	v_rcp_f32_e32 v82, v82
	v_mov_b32_dpp v177, v87 row_ror:1 row_mask:0xf bank_mask:0xf
	v_mov_b32_dpp v176, v91 row_ror:2 row_mask:0xf bank_mask:0xf
	v_mov_b32_e32 v172, v69
	v_mul_f32_e32 v82, v165, v82
	v_mul_f32_e32 v188, v164, v82
	v_cndmask_b32_e64 v165, v178, v182, s[98:99]
	v_cndmask_b32_e64 v167, v179, v183, s[100:101]
; __device__ __forceinline__ unsigned cvt_pk_bf16(float lo, float hi) { unsigned r; asm volatile("v_cvt_pk_bf16_f32 %0, %1, %2" : "=v"(r) : "v"(lo), "v"(hi)); return r; }
; __device__ __forceinline__ float siluf(float x) { return x * __builtin_amdgcn_rcpf(1.f + __expf(-x)); }
;     __device__ __forceinline__ void operator()(const f32x4 (&acc)[2][2][4][2], const pg8::Unit& u, int wr, int wc, int fr, int fq) const {
;     ...
;             for (int ai = 0; ai < 2; ++ai) {
;                 float rr[4][2];
; #pragma unroll
;                 for (int ii = 0; ii < 2; ++ii) {
;                     const int c8 = 2 * cp + ii, n = c8 >> 2, i = c8 & 3;
;                     float ua[4], ub[4], r1a[4], r2a[4], r1b[4], r2b[4];
; #pragma unroll
;                     for (int m = 0; m < 4; ++m) { ua[m] = acc[ai][0][m][n][i]; ub[m] = acc[ai][1][m][n][i];
;                         r1a[m] = dpp_ror<0x121>(ua[m]); r2a[m] = dpp_ror<0x122>(ua[m]); r1b[m] = dpp_ror<0x121>(ub[m]); r2b[m] = dpp_ror<0x122>(ub[m]); }
; #pragma unroll
;                     for (int m = 0; m < 4; ++m) {
;                         const float p1a = fr >= 1 ? r1a[m] : r1a[(m + 3) & 3], p2a = fr >= 2 ? r2a[m] : r2a[(m + 3) & 3];
;                         const float p1b = fr >= 1 ? r1b[m] : r1b[(m + 3) & 3], p2b = fr >= 2 ? r2b[m] : r2b[(m + 3) & 3];
;                         const float ca = ba[ii] + wa2[ii] * ua[m] + wa1[ii] * p1a + wa0[ii] * p2a;
;                         const float cb = bb[ii] + wb2[ii] * ub[m] + wb1[ii] * p1b + wb0[ii] * p2b;
;                         rr[m][ii] = siluf(ca) * cb;
;                     }
;                 }
; #pragma unroll
;                 for (int m = 0; m < 4; ++m) outp[ai][m][cp] = pg8::cvt_pk_bf16(rr[m][0], rr[m][1]);
	v_cndmask_b32_e64 v164, v180, v184, s[98:99]
	v_cndmask_b32_e64 v166, v181, v185, s[100:101]
	v_pk_fma_f32 v[164:165], v[174:175], v[164:165], v[170:171]
	v_pk_fma_f32 v[164:165], v[168:169], v[166:167], v[164:165]
	v_mul_f32_e32 v82, 0xbfb8aa3b, v165
	v_exp_f32_e32 v82, v82
	v_mov_b32_dpp v103, v59 row_ror:1 row_mask:0xf bank_mask:0xf
	v_mov_b32_dpp v119, v95 row_ror:1 row_mask:0xf bank_mask:0xf
	v_add_f32_e32 v82, 1.0, v82
	v_rcp_f32_e32 v82, v82
	v_mov_b32_dpp v107, v59 row_ror:2 row_mask:0xf bank_mask:0xf
	v_mul_f32_e32 v82, v165, v82
	v_mul_f32_e32 v99, v164, v82
	v_mov_b32_dpp v123, v95 row_ror:2 row_mask:0xf bank_mask:0xf
	v_mov_b32_dpp v181, v43 row_ror:1 row_mask:0xf bank_mask:0xf
	v_mov_b32_dpp v178, v87 row_ror:2 row_mask:0xf bank_mask:0xf
	v_cndmask_b32_e64 v165, v181, v103, s[98:99]
	v_mov_b32_dpp v111, v51 row_ror:1 row_mask:0xf bank_mask:0xf
	v_mov_b32_dpp v127, v91 row_ror:1 row_mask:0xf bank_mask:0xf
	v_mov_b32_dpp v182, v43 row_ror:2 row_mask:0xf bank_mask:0xf
	v_mov_b32_dpp v179, v83 row_ror:1 row_mask:0xf bank_mask:0xf
	v_cndmask_b32_e64 v167, v182, v107, s[100:101]
	v_mov_b32_dpp v115, v51 row_ror:2 row_mask:0xf bank_mask:0xf
	v_mov_b32_dpp v183, v35 row_ror:1 row_mask:0xf bank_mask:0xf
	v_mov_b32_dpp v180, v83 row_ror:2 row_mask:0xf bank_mask:0xf
	v_cndmask_b32_e64 v164, v183, v111, s[98:99]
	v_mov_b32_e32 v168, v51
	v_mov_b32_e32 v169, v59
	v_mov_b32_e32 v170, v93
	v_mov_b32_e32 v171, v89
	v_mov_b32_e32 v173, v65
	v_mov_b32_dpp v184, v35 row_ror:2 row_mask:0xf bank_mask:0xf
	v_pk_fma_f32 v[168:169], v[168:169], v[170:171], v[172:173]
	v_mov_b32_e32 v174, v85
	v_mov_b32_e32 v175, v77
	v_cndmask_b32_e64 v166, v184, v115, s[100:101]
	v_pk_fma_f32 v[164:165], v[174:175], v[164:165], v[168:169]
	v_mov_b32_e32 v168, v81
	v_mov_b32_e32 v169, v73
	v_pk_fma_f32 v[164:165], v[168:169], v[166:167], v[164:165]
	v_pk_fma_f32 v[90:91], v[94:95], v[170:171], v[172:173]
	v_mul_f32_e32 v82, 0xbfb8aa3b, v165
	v_exp_f32_e32 v82, v82
	s_nop 0
	v_add_f32_e32 v82, 1.0, v82
	v_rcp_f32_e32 v82, v82
	s_nop 0
	v_mul_f32_e32 v82, v165, v82
	v_mul_f32_e32 v185, v164, v82
	v_cndmask_b32_e64 v165, v103, v119, s[98:99]
	v_cndmask_b32_e64 v167, v107, v123, s[100:101]
	v_cndmask_b32_e64 v164, v111, v127, s[98:99]
	v_cndmask_b32_e64 v166, v115, v176, s[100:101]
	v_pk_fma_f32 v[90:91], v[174:175], v[164:165], v[90:91]
	v_pk_fma_f32 v[90:91], v[168:169], v[166:167], v[90:91]
	v_mul_f32_e32 v82, 0xbfb8aa3b, v91
	v_exp_f32_e32 v82, v82
	v_mov_b32_dpp v165, v10 row_ror:2 row_mask:0xf bank_mask:0xf
	v_mov_b32_dpp v166, v2 row_ror:1 row_mask:0xf bank_mask:0xf
	v_add_f32_e32 v82, 1.0, v82
	v_rcp_f32_e32 v82, v82
	v_mov_b32_dpp v167, v2 row_ror:2 row_mask:0xf bank_mask:0xf
	v_mul_f32_e32 v82, v91, v82
	v_mul_f32_e32 v164, v90, v82
	v_cndmask_b32_e64 v91, v119, v177, s[98:99]
	v_cndmask_b32_e64 v95, v123, v178, s[100:101]
	v_cndmask_b32_e64 v90, v127, v179, s[98:99]
	v_cndmask_b32_e64 v94, v176, v180, s[100:101]
	v_pk_fma_f32 v[82:83], v[86:87], v[170:171], v[172:173]
	s_nop 0
	v_pk_fma_f32 v[82:83], v[174:175], v[90:91], v[82:83]
	v_mov_b32_e32 v90, v35
	v_pk_fma_f32 v[82:83], v[168:169], v[94:95], v[82:83]
	v_mov_b32_e32 v91, v43
	v_mul_f32_e32 v86, 0xbfb8aa3b, v83
	v_exp_f32_e32 v86, v86
	v_pk_fma_f32 v[90:91], v[90:91], v[170:171], v[172:173]
	v_fma_f32 v172, v26, v88, v64
	v_add_f32_e32 v86, 1.0, v86
	v_rcp_f32_e32 v86, v86
	v_mov_b32_dpp v95, v74 row_ror:2 row_mask:0xf bank_mask:0xf
	v_mul_f32_e32 v83, v83, v86
	v_mul_f32_e32 v94, v82, v83
	v_cndmask_b32_e64 v83, v177, v181, s[98:99]
	v_cndmask_b32_e64 v87, v178, v182, s[100:101]
	v_cndmask_b32_e64 v82, v179, v183, s[98:99]
	v_cndmask_b32_e64 v86, v180, v184, s[100:101]
	v_pk_fma_f32 v[82:83], v[174:175], v[82:83], v[90:91]
	v_cvt_pk_bf16_f32 v111, v186, v185
	v_cvt_pk_bf16_f32 v107, v187, v164
	v_cvt_pk_bf16_f32 v103, v188, v94
	v_pk_fma_f32 v[82:83], v[168:169], v[86:87], v[82:83]
	v_mul_f32_e32 v86, 0xbfb8aa3b, v83
	v_exp_f32_e32 v86, v86
	v_mov_b32_dpp v90, v78 row_ror:1 row_mask:0xf bank_mask:0xf
	v_mov_b32_dpp v91, v78 row_ror:2 row_mask:0xf bank_mask:0xf
	v_add_f32_e32 v86, 1.0, v86
	v_rcp_f32_e32 v86, v86
	v_mov_b32_dpp v115, v70 row_ror:1 row_mask:0xf bank_mask:0xf
	v_mul_f32_e32 v83, v83, v86
	v_mul_f32_e32 v82, v82, v83
	v_cvt_pk_bf16_f32 v99, v99, v82
	v_mov_b32_dpp v119, v70 row_ror:2 row_mask:0xf bank_mask:0xf
	v_mov_b32_dpp v82, v26 row_ror:1 row_mask:0xf bank_mask:0xf
	v_mov_b32_dpp v83, v26 row_ror:2 row_mask:0xf bank_mask:0xf
	v_mov_b32_dpp v164, v10 row_ror:1 row_mask:0xf bank_mask:0xf
	v_cndmask_b32_e64 v168, v164, v82, s[98:99]
	v_cndmask_b32_e64 v169, v165, v83, s[100:101]
	v_fmac_f32_e32 v172, v76, v168
	v_fmac_f32_e32 v172, v72, v169
	v_mul_f32_e32 v169, 0xbfb8aa3b, v172
	v_exp_f32_e32 v169, v169
	v_mov_b32_dpp v86, v18 row_ror:1 row_mask:0xf bank_mask:0xf
	v_mov_b32_dpp v94, v74 row_ror:1 row_mask:0xf bank_mask:0xf
	v_add_f32_e32 v169, 1.0, v169
	v_mov_b32_dpp v87, v18 row_ror:2 row_mask:0xf bank_mask:0xf
	v_mov_b32_dpp v123, v66 row_ror:1 row_mask:0xf bank_mask:0xf
	v_rcp_f32_e32 v169, v169
	v_mov_b32_dpp v127, v66 row_ror:2 row_mask:0xf bank_mask:0xf
	v_cndmask_b32_e64 v170, v166, v86, s[98:99]
	v_fma_f32 v168, v18, v92, v68
	v_cndmask_b32_e64 v171, v167, v87, s[100:101]
	v_fmac_f32_e32 v168, v84, v170
	v_fmac_f32_e32 v168, v80, v171
	v_mul_f32_e32 v169, v172, v169
	v_mul_f32_e32 v168, v168, v169
	v_cndmask_b32_e64 v169, v82, v90, s[98:99]
	v_fma_f32 v78, v78, v88, v64
	v_cndmask_b32_e64 v170, v83, v91, s[100:101]
	v_fmac_f32_e32 v78, v76, v169
	v_fmac_f32_e32 v78, v72, v170
	v_mul_f32_e32 v169, 0xbfb8aa3b, v78
	v_exp_f32_e32 v169, v169
	s_nop 0
	v_add_f32_e32 v169, 1.0, v169
;     __device__ __forceinline__ void operator()(const f32x4 (&acc)[2][2][4][2], const pg8::Unit& u, int wr, int wc, int fr, int fq) const {
;     ...
;             for (int ai = 0; ai < 2; ++ai) {
;                 float rr[4][2];
; #pragma unroll
;                 for (int ii = 0; ii < 2; ++ii) {
;                     const int c8 = 2 * cp + ii, n = c8 >> 2, i = c8 & 3;
;                     float ua[4], ub[4], r1a[4], r2a[4], r1b[4], r2b[4];
; #pragma unroll
;                     for (int m = 0; m < 4; ++m) { ua[m] = acc[ai][0][m][n][i]; ub[m] = acc[ai][1][m][n][i];
;                         r1a[m] = dpp_ror<0x121>(ua[m]); r2a[m] = dpp_ror<0x122>(ua[m]); r1b[m] = dpp_ror<0x121>(ub[m]); r2b[m] = dpp_ror<0x122>(ub[m]); }
; #pragma unroll
;                     for (int m = 0; m < 4; ++m) {
;                         const float p1a = fr >= 1 ? r1a[m] : r1a[(m + 3) & 3], p2a = fr >= 2 ? r2a[m] : r2a[(m + 3) & 3];
;                         const float p1b = fr >= 1 ? r1b[m] : r1b[(m + 3) & 3], p2b = fr >= 2 ? r2b[m] : r2b[(m + 3) & 3];
;                         const float ca = ba[ii] + wa2[ii] * ua[m] + wa1[ii] * p1a + wa0[ii] * p2a;
;                         const float cb = bb[ii] + wb2[ii] * ub[m] + wb1[ii] * p1b + wb0[ii] * p2b;
;                         rr[m][ii] = siluf(ca) * cb;
;                     }
;                 }
; #pragma unroll
;                 for (int m = 0; m < 4; ++m) outp[ai][m][cp] = pg8::cvt_pk_bf16(rr[m][0], rr[m][1]);
;             }
;         }
; #pragma unroll
;         for (int ai = 0; ai < 2; ++ai) {
;             const int g = u.pm * 4 + ai * 2 + wr;
; #pragma unroll
;             for (int m = 0; m < 4; ++m) { const int row = g * 64 + 16 * m + fr;
;                 u32x4 w; w.x = outp[ai][m][0]; w.y = outp[ai][m][1]; w.z = outp[ai][m][2]; w.w = outp[ai][m][3];
;                 *(u32x4*)(ACTF + (size_t)row * DFF + ch0) = w; }
;             if (fr < 2) { bf16_t* p = Uf + (size_t)(g * 2 + fr) * NUP + ch0;
; #pragma unroll
;                 for (int bj = 0; bj < 2; ++bj) { const f32x4 v0 = acc[ai][bj][0][0], v1 = acc[ai][bj][0][1]; u32x4 w;
;                     w.x = pg8::cvt_pk_bf16(v0[0], v0[1]); w.y = pg8::cvt_pk_bf16(v0[2], v0[3]); w.z = pg8::cvt_pk_bf16(v1[0], v1[1]); w.w = pg8::cvt_pk_bf16(v1[2], v1[3]);
;                     *(u32x4*)(p + bj * DFF) = w; } }
	v_rcp_f32_e32 v169, v169
	v_cndmask_b32_e64 v171, v86, v94, s[98:99]
	v_fma_f32 v74, v74, v92, v68
	v_cndmask_b32_e64 v172, v87, v95, s[100:101]
	v_fmac_f32_e32 v74, v84, v171
	v_fmac_f32_e32 v74, v80, v172
	v_mul_f32_e32 v78, v78, v169
	v_mul_f32_e32 v74, v74, v78
	v_cndmask_b32_e64 v78, v90, v115, s[98:99]
	v_fma_f32 v70, v70, v88, v64
	v_cndmask_b32_e64 v169, v91, v119, s[100:101]
	v_fmac_f32_e32 v70, v76, v78
	v_fmac_f32_e32 v70, v72, v169
	v_mul_f32_e32 v78, 0xbfb8aa3b, v70
	v_exp_f32_e32 v78, v78
	s_nop 0
	v_add_f32_e32 v78, 1.0, v78
	v_rcp_f32_e32 v78, v78
	v_cndmask_b32_e64 v170, v94, v123, s[98:99]
	v_fma_f32 v66, v66, v92, v68
	v_cndmask_b32_e64 v171, v95, v127, s[100:101]
	v_fmac_f32_e32 v66, v84, v170
	v_fmac_f32_e32 v66, v80, v171
	v_mul_f32_e32 v70, v70, v78
	v_mul_f32_e32 v66, v66, v70
	v_cndmask_b32_e64 v70, v115, v164, s[98:99]
	v_fma_f32 v64, v10, v88, v64
	v_cndmask_b32_e64 v78, v119, v165, s[100:101]
	v_fmac_f32_e32 v64, v76, v70
	v_fmac_f32_e32 v64, v72, v78
	v_mul_f32_e32 v70, 0xbfb8aa3b, v64
	v_exp_f32_e32 v70, v70
	s_nop 0
	v_add_f32_e32 v70, 1.0, v70
	v_rcp_f32_e32 v70, v70
	v_cndmask_b32_e64 v82, v123, v166, s[98:99]
	v_fma_f32 v68, v2, v92, v68
	v_cndmask_b32_e64 v83, v127, v167, s[100:101]
	v_fmac_f32_e32 v68, v84, v82
	v_fmac_f32_e32 v68, v80, v83
	v_mul_f32_e32 v64, v64, v70
	v_mul_f32_e32 v64, v68, v64
	v_mov_b32_dpp v68, v27 row_ror:1 row_mask:0xf bank_mask:0xf
	v_mov_b32_dpp v78, v79 row_ror:1 row_mask:0xf bank_mask:0xf
	v_mov_b32_dpp v70, v27 row_ror:2 row_mask:0xf bank_mask:0xf
	v_mov_b32_dpp v80, v79 row_ror:2 row_mask:0xf bank_mask:0xf
	v_mov_b32_dpp v84, v71 row_ror:1 row_mask:0xf bank_mask:0xf
	v_mov_b32_dpp v86, v71 row_ror:2 row_mask:0xf bank_mask:0xf
	v_mov_b32_dpp v90, v11 row_ror:1 row_mask:0xf bank_mask:0xf
	v_mov_b32_dpp v91, v11 row_ror:2 row_mask:0xf bank_mask:0xf
	v_cndmask_b32_e64 v95, v90, v68, s[98:99]
	v_fma_f32 v127, v27, v89, v65
	v_cndmask_b32_e64 v115, v91, v70, s[100:101]
	v_fmac_f32_e32 v127, v77, v95
	v_fmac_f32_e32 v127, v73, v115
	v_mul_f32_e32 v115, 0xbfb8aa3b, v127
	v_exp_f32_e32 v115, v115
	v_mov_b32_dpp v72, v19 row_ror:1 row_mask:0xf bank_mask:0xf
	v_mov_b32_dpp v82, v75 row_ror:1 row_mask:0xf bank_mask:0xf
	v_add_f32_e32 v115, 1.0, v115
	v_mov_b32_dpp v76, v19 row_ror:2 row_mask:0xf bank_mask:0xf
	v_mov_b32_dpp v83, v75 row_ror:2 row_mask:0xf bank_mask:0xf
	v_mov_b32_dpp v87, v67 row_ror:1 row_mask:0xf bank_mask:0xf
	v_rcp_f32_e32 v115, v115
	v_mov_b32_dpp v88, v67 row_ror:2 row_mask:0xf bank_mask:0xf
	v_mov_b32_dpp v92, v3 row_ror:1 row_mask:0xf bank_mask:0xf
	v_mov_b32_dpp v94, v3 row_ror:2 row_mask:0xf bank_mask:0xf
	v_cndmask_b32_e64 v119, v92, v72, s[98:99]
	v_fma_f32 v95, v19, v93, v69
	v_cndmask_b32_e64 v123, v94, v76, s[100:101]
	v_fmac_f32_e32 v95, v85, v119
	v_fmac_f32_e32 v95, v81, v123
	v_mul_f32_e32 v115, v127, v115
	v_mul_f32_e32 v95, v95, v115
	v_cndmask_b32_e64 v115, v68, v78, s[98:99]
	v_fma_f32 v79, v79, v89, v65
	v_cndmask_b32_e64 v119, v70, v80, s[100:101]
	v_fmac_f32_e32 v79, v77, v115
	v_fmac_f32_e32 v79, v73, v119
	v_mul_f32_e32 v115, 0xbfb8aa3b, v79
	v_exp_f32_e32 v115, v115
	s_nop 0
	v_add_f32_e32 v115, 1.0, v115
	v_rcp_f32_e32 v115, v115
	v_cndmask_b32_e64 v123, v72, v82, s[98:99]
	v_fma_f32 v75, v75, v93, v69
	v_cndmask_b32_e64 v127, v76, v83, s[100:101]
	v_fmac_f32_e32 v75, v85, v123
	v_fmac_f32_e32 v75, v81, v127
	v_mul_f32_e32 v79, v79, v115
	v_mul_f32_e32 v75, v75, v79
	v_cndmask_b32_e64 v79, v78, v84, s[98:99]
	v_fma_f32 v71, v71, v89, v65
	v_cndmask_b32_e64 v115, v80, v86, s[100:101]
	v_fmac_f32_e32 v71, v77, v79
	v_fmac_f32_e32 v71, v73, v115
	v_mul_f32_e32 v79, 0xbfb8aa3b, v71
	v_exp_f32_e32 v79, v79
	v_cndmask_b32_e64 v68, v84, v90, s[98:99]
	v_fmac_f32_e32 v65, v11, v89
	v_cndmask_b32_e64 v70, v86, v91, s[100:101]
	v_fmac_f32_e32 v65, v77, v68
	v_fmac_f32_e32 v65, v73, v70
	v_add_f32_e32 v79, 1.0, v79
	v_mul_f32_e32 v68, 0xbfb8aa3b, v65
	v_rcp_f32_e32 v79, v79
	v_exp_f32_e32 v68, v68
	v_cndmask_b32_e64 v119, v82, v87, s[98:99]
	v_fma_f32 v67, v67, v93, v69
	v_cndmask_b32_e64 v123, v83, v88, s[100:101]
	v_fmac_f32_e32 v67, v85, v119
	v_fmac_f32_e32 v67, v81, v123
	v_mul_f32_e32 v71, v71, v79
	v_add_f32_e32 v68, 1.0, v68
	v_mul_f32_e32 v67, v67, v71
	v_rcp_f32_e32 v68, v68
	v_cndmask_b32_e64 v71, v87, v92, s[98:99]
	v_fmac_f32_e32 v69, v3, v93
	v_cndmask_b32_e64 v72, v88, v94, s[100:101]
	v_fmac_f32_e32 v69, v85, v71
	v_readlane_b32 s8, v255, 42
	v_fmac_f32_e32 v69, v81, v72
	v_mul_f32_e32 v65, v65, v68
	s_add_i32 s11, s11, s8
	v_mul_f32_e32 v65, v69, v65
	v_cvt_pk_bf16_f32 v127, v168, v95
	v_cvt_pk_bf16_f32 v123, v74, v75
	v_cvt_pk_bf16_f32 v119, v66, v67
	v_lshl_or_b32 v70, s11, 6, v129
	v_mov_b64_e32 v[66:67], s[70:71]
	v_cvt_pk_bf16_f32 v115, v64, v65
	v_mad_i64_i32 v[68:69], s[8:9], v70, s5, v[66:67]
	v_lshlrev_b64 v[64:65], 1, v[162:163]
	v_lshl_add_u64 v[68:69], v[68:69], 0, v[64:65]
	global_store_dwordx4 v[68:69], v[108:111], off
	v_or_b32_e32 v68, 16, v70
	v_mad_i64_i32 v[68:69], s[8:9], v68, s5, v[66:67]
	v_lshl_add_u64 v[68:69], v[68:69], 0, v[64:65]
	global_store_dwordx4 v[68:69], v[104:107], off
	v_or_b32_e32 v68, 32, v70
	v_mad_i64_i32 v[68:69], s[8:9], v68, s5, v[66:67]
	v_lshl_add_u64 v[68:69], v[68:69], 0, v[64:65]
	global_store_dwordx4 v[68:69], v[100:103], off
	v_or_b32_e32 v68, 48, v70
	v_mad_i64_i32 v[66:67], s[8:9], v68, s5, v[66:67]
	v_lshl_add_u64 v[66:67], v[66:67], 0, v[64:65]
	global_store_dwordx4 v[66:67], v[96:99], off
	s_and_saveexec_b64 s[8:9], s[86:87]
	s_movk_i32 s14, 0x5800
	s_cbranch_execz .LBB0_2213
	v_readlane_b32 s12, v255, 33
	v_readlane_b32 s13, v255, 34
	v_lshl_or_b32 v68, s11, 1, v129
	v_cvt_pk_bf16_f32 v60, v60, v61
	v_cvt_pk_bf16_f32 v61, v62, v63
	v_cvt_pk_bf16_f32 v62, v56, v57
	v_cvt_pk_bf16_f32 v63, v58, v59
	s_nop 0
	v_mov_b64_e32 v[66:67], s[12:13]
	v_mad_i64_i32 v[66:67], s[12:13], v68, s14, v[66:67]
	v_lshl_add_u64 v[66:67], v[162:163], 1, v[66:67]
	global_store_dwordx4 v[66:67], v[60:63], off
	v_cvt_pk_bf16_f32 v52, v52, v53
	v_cvt_pk_bf16_f32 v53, v54, v55
	v_cvt_pk_bf16_f32 v54, v48, v49
	v_add_co_u32_e32 v48, vcc, 0x2000, v66
	v_cvt_pk_bf16_f32 v55, v50, v51
	s_nop 1
	v_addc_co_u32_e32 v49, vcc, 0, v67, vcc
	global_store_dwordx4 v[48:49], v[52:55], off offset:3072
